# baseline (speedup 1.0000x reference)
;     ...
;   for (int kt = 0; kt < nk; ++kt) {
;     const int kn = (kt + 1 < nk) ? kt + 1 : kt;
;     GM_LOAD2(kn * 64, kn * bkstep)
;     __builtin_amdgcn_sched_barrier(0);
;     const char* As = smem + (kt & 1) * 2 * TILE_B;
;     const char* Bs = As + TILE_B;
;     if constexpr (HOIST) {
;       bf16x8 fa0[4], fa1[4], fb0[4], fb1[4];
; #pragma unroll
;       for (int st = 0; st < 4; ++st) {
;         fa0[st] = *(const bf16x8*)(As + aoff + st * 32);
;         fb0[st] = *(const bf16x8*)(Bs + boff + st * 32);
;         fa1[st] = *(const bf16x8*)(As + aoff + 32 * LSTR + st * 32);
;         fb1[st] = *(const bf16x8*)(Bs + boff + 32 * LSTR + st * 32);
;       }
;       __builtin_amdgcn_sched_barrier(0);
; #pragma unroll
;       for (int st = 0; st < 4; ++st) {
;         acc[0][0] = mfma32(fa0[st], fb0[st], acc[0][0]);
;         acc[0][1] = mfma32(fa0[st], fb1[st], acc[0][1]);
;         acc[1][0] = mfma32(fa1[st], fb0[st], acc[1][0]);
;         acc[1][1] = mfma32(fa1[st], fb1[st], acc[1][1]);
;       }
;     } else {
; #pragma unroll
;       for (int st = 0; st < 4; ++st) {
;         bf16x8 a0 = *(const bf16x8*)(As + aoff + st * 32);
;         bf16x8 a1 = *(const bf16x8*)(As + aoff + 32 * LSTR + st * 32);
;         bf16x8 b0 = *(const bf16x8*)(Bs + boff + st * 32);
;         bf16x8 b1 = *(const bf16x8*)(Bs + boff + 32 * LSTR + st * 32);
;         acc[0][0] = mfma32(a0, b0, acc[0][0]);
;         acc[0][1] = mfma32(a0, b1, acc[0][1]);
;         acc[1][0] = mfma32(a1, b0, acc[1][0]);
;         acc[1][1] = mfma32(a1, b1, acc[1][1]);
;       }
;     }
;     __builtin_amdgcn_sched_barrier(0);
;     {
;       char* Ad = smem + ((kt + 1) & 1) * 2 * TILE_B;
;       GM_STORE(Ad)
;     }
;     __syncthreads();
;   }
.LBB0_360:
	s_and_b32 s25, s14, 2
	s_mulk_i32 s25, 0x4800
	v_add3_u32 v197, s25, v191, v192
	s_setprio 1
	v_add3_u32 v223, s25, v193, v192
	ds_read_b128 v[232:235], v197 offset:0
	ds_read_b128 v[236:239], v223 offset:18432
	ds_read_b128 v[244:247], v197 offset:4608
	ds_read_b128 v[240:243], v223 offset:23040
	s_waitcnt lgkmcnt(2)
	v_mfma_f32_32x32x16_bf16 v[50:65], v[232:235], v[236:239], v[50:65]
	ds_read_b128 v[248:251], v197 offset:32
	s_waitcnt lgkmcnt(2)
	v_mfma_f32_32x32x16_bf16 v[2:17], v[244:247], v[236:239], v[2:17]
	ds_read_b128 v[236:239], v223 offset:18464
	s_waitcnt lgkmcnt(2)
	v_mfma_f32_32x32x16_bf16 v[18:33], v[232:235], v[240:243], v[18:33]
	ds_read_b128 v[232:235], v197 offset:4640
	v_mfma_f32_32x32x16_bf16 v[34:49], v[244:247], v[240:243], v[34:49]
	ds_read_b128 v[240:243], v223 offset:23072
	s_waitcnt lgkmcnt(2)
	v_mfma_f32_32x32x16_bf16 v[50:65], v[248:251], v[236:239], v[50:65]
	ds_read_b128 v[244:247], v197 offset:64
	s_waitcnt lgkmcnt(2)
	v_mfma_f32_32x32x16_bf16 v[2:17], v[232:235], v[236:239], v[2:17]
	ds_read_b128 v[236:239], v223 offset:18496
	s_waitcnt lgkmcnt(2)
	v_mfma_f32_32x32x16_bf16 v[18:33], v[248:251], v[240:243], v[18:33]
	ds_read_b128 v[248:251], v197 offset:4672
	v_mfma_f32_32x32x16_bf16 v[34:49], v[232:235], v[240:243], v[34:49]
	ds_read_b128 v[240:243], v223 offset:23104
	s_waitcnt lgkmcnt(2)
	v_mfma_f32_32x32x16_bf16 v[50:65], v[244:247], v[236:239], v[50:65]
	ds_read_b128 v[232:235], v197 offset:96
	s_waitcnt lgkmcnt(2)
	v_mfma_f32_32x32x16_bf16 v[2:17], v[248:251], v[236:239], v[2:17]
	ds_read_b128 v[236:239], v223 offset:18528
	s_waitcnt lgkmcnt(2)
	v_mfma_f32_32x32x16_bf16 v[18:33], v[244:247], v[240:243], v[18:33]
	ds_read_b128 v[244:247], v197 offset:4704
	v_mfma_f32_32x32x16_bf16 v[34:49], v[248:251], v[240:243], v[34:49]
	ds_read_b128 v[240:243], v223 offset:23136
	s_waitcnt lgkmcnt(2)
	v_mfma_f32_32x32x16_bf16 v[50:65], v[232:235], v[236:239], v[50:65]
	s_waitcnt lgkmcnt(1)
	v_mfma_f32_32x32x16_bf16 v[2:17], v[244:247], v[236:239], v[2:17]
	s_waitcnt lgkmcnt(0)
	v_mfma_f32_32x32x16_bf16 v[18:33], v[232:235], v[240:243], v[18:33]
	v_mfma_f32_32x32x16_bf16 v[34:49], v[244:247], v[240:243], v[34:49]
	s_add_i32 s14, s14, 2
	s_and_b32 s25, s14, 2
	s_mulk_i32 s25, 0x4800
	s_add_i32 s15, s15, -1
	s_add_i32 s6, s6, 64
	v_add_u32_e32 v197, s25, v190
	s_lshl_b64 s[26:27], s[6:7], 1
	s_cmp_lg_u32 s15, 0
	s_waitcnt vmcnt(7)
	ds_write_b128 v197, v[198:201]
	v_lshl_add_u64 v[198:199], v[158:159], 0, s[26:27]
	global_load_dwordx4 v[198:201], v[198:199], off
	s_waitcnt vmcnt(7)
	ds_write_b128 v197, v[202:205] offset:4608
	v_lshl_add_u64 v[202:203], v[160:161], 0, s[26:27]
	global_load_dwordx4 v[202:205], v[202:203], off
	s_waitcnt vmcnt(7)
	ds_write_b128 v197, v[206:209] offset:9216
	v_lshl_add_u64 v[206:207], v[162:163], 0, s[26:27]
	global_load_dwordx4 v[206:209], v[206:207], off
	s_waitcnt vmcnt(7)
	ds_write_b128 v197, v[210:213] offset:13824
	v_lshl_add_u64 v[210:211], v[164:165], 0, s[26:27]
	global_load_dwordx4 v[210:213], v[210:211], off
	s_waitcnt vmcnt(7)
	ds_write_b128 v197, v[214:217] offset:18432
	v_lshl_add_u64 v[214:215], v[166:167], 0, s[26:27]
	global_load_dwordx4 v[214:217], v[214:215], off
	s_waitcnt vmcnt(7)
	ds_write_b128 v197, v[218:221] offset:23040
	v_lshl_add_u64 v[218:219], v[168:169], 0, s[26:27]
	global_load_dwordx4 v[218:221], v[218:219], off
	s_waitcnt vmcnt(7)
	ds_write_b128 v197, v[224:227] offset:27648
	v_lshl_add_u64 v[224:225], v[170:171], 0, s[26:27]
	global_load_dwordx4 v[224:227], v[224:225], off
	s_waitcnt vmcnt(7)
	ds_write_b128 v197, v[228:231] offset:32256
	v_lshl_add_u64 v[228:229], v[172:173], 0, s[26:27]
	global_load_dwordx4 v[228:231], v[228:229], off
	s_setprio 0
	s_waitcnt lgkmcnt(0)
	s_barrier
	s_cbranch_scc1 .LBB0_360
	s_and_b32 s25, s14, 2
	s_mulk_i32 s25, 0x4800
	v_add3_u32 v197, s25, v191, v192
	s_setprio 1
	v_add3_u32 v223, s25, v193, v192
	ds_read_b128 v[232:235], v197 offset:0
	ds_read_b128 v[236:239], v223 offset:18432
	ds_read_b128 v[244:247], v197 offset:4608
	ds_read_b128 v[240:243], v223 offset:23040
	s_waitcnt lgkmcnt(2)
	v_mfma_f32_32x32x16_bf16 v[50:65], v[232:235], v[236:239], v[50:65]
	ds_read_b128 v[248:251], v197 offset:32
	s_waitcnt lgkmcnt(2)
	v_mfma_f32_32x32x16_bf16 v[2:17], v[244:247], v[236:239], v[2:17]
	ds_read_b128 v[236:239], v223 offset:18464
	s_waitcnt lgkmcnt(2)
	v_mfma_f32_32x32x16_bf16 v[18:33], v[232:235], v[240:243], v[18:33]
	ds_read_b128 v[232:235], v197 offset:4640
	v_mfma_f32_32x32x16_bf16 v[34:49], v[244:247], v[240:243], v[34:49]
	ds_read_b128 v[240:243], v223 offset:23072
	s_waitcnt lgkmcnt(2)
	v_mfma_f32_32x32x16_bf16 v[50:65], v[248:251], v[236:239], v[50:65]
	ds_read_b128 v[244:247], v197 offset:64
	s_waitcnt lgkmcnt(2)
	v_mfma_f32_32x32x16_bf16 v[2:17], v[232:235], v[236:239], v[2:17]
	ds_read_b128 v[236:239], v223 offset:18496
	s_waitcnt lgkmcnt(2)
	v_mfma_f32_32x32x16_bf16 v[18:33], v[248:251], v[240:243], v[18:33]
	ds_read_b128 v[248:251], v197 offset:4672
	v_mfma_f32_32x32x16_bf16 v[34:49], v[232:235], v[240:243], v[34:49]
	ds_read_b128 v[240:243], v223 offset:23104
	s_waitcnt lgkmcnt(2)
	v_mfma_f32_32x32x16_bf16 v[50:65], v[244:247], v[236:239], v[50:65]
	ds_read_b128 v[232:235], v197 offset:96
	s_waitcnt lgkmcnt(2)
	v_mfma_f32_32x32x16_bf16 v[2:17], v[248:251], v[236:239], v[2:17]
	ds_read_b128 v[236:239], v223 offset:18528
	s_waitcnt lgkmcnt(2)
	v_mfma_f32_32x32x16_bf16 v[18:33], v[244:247], v[240:243], v[18:33]
	ds_read_b128 v[244:247], v197 offset:4704
	v_mfma_f32_32x32x16_bf16 v[34:49], v[248:251], v[240:243], v[34:49]
	ds_read_b128 v[240:243], v223 offset:23136
	s_waitcnt lgkmcnt(2)
	v_mfma_f32_32x32x16_bf16 v[50:65], v[232:235], v[236:239], v[50:65]
	s_waitcnt lgkmcnt(1)
	v_mfma_f32_32x32x16_bf16 v[2:17], v[244:247], v[236:239], v[2:17]
	s_waitcnt lgkmcnt(0)
	v_mfma_f32_32x32x16_bf16 v[18:33], v[232:235], v[240:243], v[18:33]
	v_mfma_f32_32x32x16_bf16 v[34:49], v[244:247], v[240:243], v[34:49]
	s_add_i32 s14, s14, 2
	s_and_b32 s25, s14, 2
	s_mulk_i32 s25, 0x4800
	s_add_i32 s6, s6, 64
	v_add_u32_e32 v197, s25, v190
	s_waitcnt vmcnt(7)
	ds_write_b128 v197, v[198:201]
	s_waitcnt vmcnt(6)
	ds_write_b128 v197, v[202:205] offset:4608
	s_waitcnt vmcnt(5)
	ds_write_b128 v197, v[206:209] offset:9216
	s_waitcnt vmcnt(4)
	ds_write_b128 v197, v[210:213] offset:13824
	s_waitcnt vmcnt(3)
	ds_write_b128 v197, v[214:217] offset:18432
	s_waitcnt vmcnt(2)
	ds_write_b128 v197, v[218:221] offset:23040
	s_waitcnt vmcnt(1)
	ds_write_b128 v197, v[224:227] offset:27648
	s_waitcnt vmcnt(0)
	ds_write_b128 v197, v[228:231] offset:32256
	s_setprio 0
	s_waitcnt lgkmcnt(0)
	s_barrier
; __device__ __forceinline__ void acc_to_lds(const f32x16 (&acc)[2][2], float* cs) {
;   const int tid = threadIdx.x, lane = tid & 63, wave = tid >> 6;
;   const int wm = wave >> 1, wn = wave & 1;
; #pragma unroll
;   for (int i = 0; i < 2; ++i)
; #pragma unroll
;     for (int j = 0; j < 2; ++j)
; #pragma unroll
;       for (int r = 0; r < 16; ++r) {
;         int row = wm * 64 + i * 32 + (r & 3) + 8 * (r >> 2) + 4 * (lane >> 5);
;         int col = wn * 64 + j * 32 + (lane & 31);
;         cs[row * CSTR + col] = acc[i][j][r];
;       }
;   __syncthreads();
; __device__ __forceinline__ void fourier_half_tile(const Params& P, bool isctx, int b, int mt, int nt, char* smem) {
;     ...
;       u16* d1 = WSP(u16, OFF_FTO) + (rowbase + k) * 256 + nt * 128 + half * 64;
;       u16* d2 = WSP(u16, OFF_FTO) + (rowbase + (k > 0 ? N - k : 0)) * 256 + nt * 128 + half * 64;
; #pragma unroll
;       for (int q = 0; q < 8; ++q) {
;         float4 a = *(const float4*)(cs + r * CSTR + half * 64 + q * 8);
;         float4 c = *(const float4*)(cs + r * CSTR + half * 64 + q * 8 + 4);
;         uint4 o1, o2;
;         o1.x = pack2(pacc[q * 8 + 0] + a.x, pacc[q * 8 + 1] + a.y); o1.y = pack2(pacc[q * 8 + 2] + a.z, pacc[q * 8 + 3] + a.w);
;         o1.z = pack2(pacc[q * 8 + 4] + c.x, pacc[q * 8 + 5] + c.y); o1.w = pack2(pacc[q * 8 + 6] + c.z, pacc[q * 8 + 7] + c.w);
;         o2.x = pack2(pacc[q * 8 + 0] - a.x, pacc[q * 8 + 1] - a.y); o2.y = pack2(pacc[q * 8 + 2] - a.z, pacc[q * 8 + 3] - a.w);
;         o2.z = pack2(pacc[q * 8 + 4] - c.x, pacc[q * 8 + 5] - c.y); o2.w = pack2(pacc[q * 8 + 6] - c.z, pacc[q * 8 + 7] - c.w);
;         *(uint4*)(d1 + q * 8) = o1;
;         if (k > 0) *(uint4*)(d2 + q * 8) = o2;
	s_nop 0
	s_nop 0
	s_nop 0
	v_add3_u32 v197, s25, v191, v192
	s_setprio 1
	v_add3_u32 v223, s25, v193, v192
	ds_read_b128 v[198:201], v197 offset:0
	ds_read_b128 v[202:205], v223 offset:18432
	ds_read_b128 v[210:213], v197 offset:4608
	ds_read_b128 v[206:209], v223 offset:23040
	s_waitcnt lgkmcnt(2)
	v_mfma_f32_32x32x16_bf16 v[50:65], v[198:201], v[202:205], v[50:65]
	ds_read_b128 v[214:217], v197 offset:32
	s_waitcnt lgkmcnt(2)
	v_mfma_f32_32x32x16_bf16 v[2:17], v[210:213], v[202:205], v[2:17]
	ds_read_b128 v[202:205], v223 offset:18464
	s_waitcnt lgkmcnt(2)
	v_mfma_f32_32x32x16_bf16 v[18:33], v[198:201], v[206:209], v[18:33]
	ds_read_b128 v[198:201], v197 offset:4640
	v_mfma_f32_32x32x16_bf16 v[34:49], v[210:213], v[206:209], v[34:49]
	ds_read_b128 v[206:209], v223 offset:23072
	s_waitcnt lgkmcnt(2)
	v_mfma_f32_32x32x16_bf16 v[50:65], v[214:217], v[202:205], v[50:65]
	ds_read_b128 v[210:213], v197 offset:64
	s_waitcnt lgkmcnt(2)
	v_mfma_f32_32x32x16_bf16 v[2:17], v[198:201], v[202:205], v[2:17]
	ds_read_b128 v[202:205], v223 offset:18496
	s_waitcnt lgkmcnt(2)
	v_mfma_f32_32x32x16_bf16 v[18:33], v[214:217], v[206:209], v[18:33]
	ds_read_b128 v[214:217], v197 offset:4672
	v_mfma_f32_32x32x16_bf16 v[34:49], v[198:201], v[206:209], v[34:49]
	ds_read_b128 v[206:209], v223 offset:23104
	s_waitcnt lgkmcnt(2)
	v_mfma_f32_32x32x16_bf16 v[50:65], v[210:213], v[202:205], v[50:65]
	ds_read_b128 v[198:201], v197 offset:96
	s_waitcnt lgkmcnt(2)
	v_mfma_f32_32x32x16_bf16 v[2:17], v[214:217], v[202:205], v[2:17]
	ds_read_b128 v[202:205], v223 offset:18528
	s_waitcnt lgkmcnt(2)
	v_mfma_f32_32x32x16_bf16 v[18:33], v[210:213], v[206:209], v[18:33]
	ds_read_b128 v[210:213], v197 offset:4704
	v_mfma_f32_32x32x16_bf16 v[34:49], v[214:217], v[206:209], v[34:49]
	ds_read_b128 v[206:209], v223 offset:23136
	s_waitcnt lgkmcnt(2)
	v_mfma_f32_32x32x16_bf16 v[50:65], v[198:201], v[202:205], v[50:65]
	s_waitcnt lgkmcnt(1)
	v_mfma_f32_32x32x16_bf16 v[2:17], v[210:213], v[202:205], v[2:17]
	s_waitcnt lgkmcnt(0)
	v_mfma_f32_32x32x16_bf16 v[18:33], v[198:201], v[206:209], v[18:33]
	v_mfma_f32_32x32x16_bf16 v[34:49], v[210:213], v[206:209], v[34:49]
	s_setprio 0
	s_waitcnt lgkmcnt(0)
	s_barrier
	ds_write2_b32 v194, v50, v18 offset1:32
	ds_write2_b32 v194, v51, v19 offset0:132 offset1:164
	v_add_u32_e32 v18, 0x400, v194
	ds_write2_b32 v18, v52, v20 offset0:8 offset1:40
	ds_write2_b32 v18, v53, v21 offset0:140 offset1:172
	v_add_u32_e32 v18, 0x1000, v194
	ds_write2_b32 v18, v54, v22 offset0:32 offset1:64
	ds_write2_b32 v18, v55, v23 offset0:164 offset1:196
	v_add_u32_e32 v18, 0x1400, v194
	ds_write2_b32 v18, v56, v24 offset0:40 offset1:72
	ds_write2_b32 v18, v57, v25 offset0:172 offset1:204
	v_add_u32_e32 v18, 0x2000, v194
	ds_write2_b32 v18, v58, v26 offset0:64 offset1:96
	ds_write2_b32 v18, v59, v27 offset0:196 offset1:228
	v_add_u32_e32 v18, 0x2400, v194
	ds_write2_b32 v18, v60, v28 offset0:72 offset1:104
	ds_write2_b32 v18, v61, v29 offset0:204 offset1:236
	v_add_u32_e32 v18, 0x3000, v194
	ds_write2_b32 v18, v62, v30 offset0:96 offset1:128
	v_add_u32_e32 v18, 0x3200, v194
	ds_write2_b32 v18, v63, v31 offset0:100 offset1:132
	v_add_u32_e32 v18, 0x3400, v194
	ds_write2_b32 v18, v64, v32 offset0:104 offset1:136
	v_add_u32_e32 v18, 0x3600, v194
	ds_write2_b32 v18, v65, v33 offset0:108 offset1:140
	v_add_u32_e32 v18, 0x4000, v194
	ds_write2_b32 v18, v2, v34 offset0:128 offset1:160
	v_add_u32_e32 v2, 0x4400, v194
	ds_write2_b32 v2, v3, v35 offset0:4 offset1:36
	ds_write2_b32 v2, v4, v36 offset0:136 offset1:168
	v_add_u32_e32 v2, 0x4800, v194
	ds_write2_b32 v2, v5, v37 offset0:12 offset1:44
	v_add_u32_e32 v2, 0x5000, v194
	ds_write2_b32 v2, v6, v38 offset0:160 offset1:192
	v_add_u32_e32 v2, 0x5400, v194
	ds_write2_b32 v2, v7, v39 offset0:36 offset1:68
	ds_write2_b32 v2, v8, v40 offset0:168 offset1:200
	v_add_u32_e32 v2, 0x5800, v194
	ds_write2_b32 v2, v9, v41 offset0:44 offset1:76
	v_add_u32_e32 v2, 0x6000, v194
	ds_write2_b32 v2, v10, v42 offset0:192 offset1:224
	v_add_u32_e32 v2, 0x6400, v194
	ds_write2_b32 v2, v11, v43 offset0:68 offset1:100
	ds_write2_b32 v2, v12, v44 offset0:200 offset1:232
	v_add_u32_e32 v2, 0x6800, v194
	ds_write2_b32 v2, v13, v45 offset0:76 offset1:108
	v_add_u32_e32 v2, 0x7200, v194
	ds_write2_b32 v2, v14, v46 offset0:96 offset1:128
	v_add_u32_e32 v2, 0x7400, v194
	ds_write2_b32 v2, v15, v47 offset0:100 offset1:132
	v_add_u32_e32 v2, 0x7600, v194
	ds_write2_b32 v2, v16, v48 offset0:104 offset1:136
	v_add_u32_e32 v2, 0x7800, v194
	s_mov_b64 s[14:15], -1
	s_and_b64 vcc, exec, s[12:13]
	ds_write2_b32 v2, v17, v49 offset0:108 offset1:140
	s_waitcnt lgkmcnt(0)
	s_barrier
	s_cbranch_vccz .LBB0_379
	ds_read_b128 v[2:5], v195
	ds_read_b128 v[6:9], v195 offset:16
	s_waitcnt lgkmcnt(1)
	v_add_f32_e32 v10, v78, v2
	v_add_f32_e32 v11, v79, v3
	v_sub_f32_e32 v2, v78, v2
	v_sub_f32_e32 v3, v79, v3
	v_add_f32_e32 v12, v80, v4
	v_add_f32_e32 v13, v81, v5
	v_cvt_pk_bf16_f32 v2, v2, v3
	v_sub_f32_e32 v3, v80, v4
	v_sub_f32_e32 v4, v81, v5
	v_cvt_pk_bf16_f32 v10, v10, v11
	v_cvt_pk_bf16_f32 v11, v12, v13
	s_waitcnt lgkmcnt(0)
	v_add_f32_e32 v12, v74, v6
	v_add_f32_e32 v13, v75, v7
	v_cvt_pk_bf16_f32 v3, v3, v4
	v_sub_f32_e32 v4, v74, v6
	v_sub_f32_e32 v5, v75, v7
	v_cvt_pk_bf16_f32 v12, v12, v13
	v_add_f32_e32 v13, v76, v8
	v_cvt_pk_bf16_f32 v4, v4, v5
	v_sub_f32_e32 v5, v76, v8
	v_add_f32_e32 v14, v77, v9
	v_cvt_pk_bf16_f32 v13, v13, v14
	v_sub_f32_e32 v6, v77, v9
	v_cvt_pk_bf16_f32 v5, v5, v6
	global_store_dwordx4 v[148:149], v[10:13], off
	s_and_saveexec_b64 s[14:15], s[2:3]
	s_cbranch_execz .LBB0_364
	global_store_dwordx4 v[150:151], v[2:5], off

;     ...
;   for (int kt = 0; kt < nk; ++kt) {
;     const int kn = (kt + 1 < nk) ? kt + 1 : kt;
;     GM_LOAD2(kn * 64, kn * bkstep)
;     __builtin_amdgcn_sched_barrier(0);
;     const char* As = smem + (kt & 1) * 2 * TILE_B;
;     const char* Bs = As + TILE_B;
;     if constexpr (HOIST) {
;       bf16x8 fa0[4], fa1[4], fb0[4], fb1[4];
; #pragma unroll
;       for (int st = 0; st < 4; ++st) {
;         fa0[st] = *(const bf16x8*)(As + aoff + st * 32);
;         fb0[st] = *(const bf16x8*)(Bs + boff + st * 32);
;         fa1[st] = *(const bf16x8*)(As + aoff + 32 * LSTR + st * 32);
;         fb1[st] = *(const bf16x8*)(Bs + boff + 32 * LSTR + st * 32);
;       }
;       __builtin_amdgcn_sched_barrier(0);
; #pragma unroll
;       for (int st = 0; st < 4; ++st) {
;         acc[0][0] = mfma32(fa0[st], fb0[st], acc[0][0]);
;         acc[0][1] = mfma32(fa0[st], fb1[st], acc[0][1]);
;         acc[1][0] = mfma32(fa1[st], fb0[st], acc[1][0]);
;         acc[1][1] = mfma32(fa1[st], fb1[st], acc[1][1]);
;       }
;     } else {
; #pragma unroll
;       for (int st = 0; st < 4; ++st) {
;         bf16x8 a0 = *(const bf16x8*)(As + aoff + st * 32);
;         bf16x8 a1 = *(const bf16x8*)(As + aoff + 32 * LSTR + st * 32);
;         bf16x8 b0 = *(const bf16x8*)(Bs + boff + st * 32);
;         bf16x8 b1 = *(const bf16x8*)(Bs + boff + 32 * LSTR + st * 32);
;         acc[0][0] = mfma32(a0, b0, acc[0][0]);
;         acc[0][1] = mfma32(a0, b1, acc[0][1]);
;         acc[1][0] = mfma32(a1, b0, acc[1][0]);
;         acc[1][1] = mfma32(a1, b1, acc[1][1]);
;       }
;     }
;     __builtin_amdgcn_sched_barrier(0);
;     {
;       char* Ad = smem + ((kt + 1) & 1) * 2 * TILE_B;
;       GM_STORE(Ad)
;     }
;     __syncthreads();
;   }
.LBB0_632:
	s_and_b32 s38, s37, 2
	s_mulk_i32 s38, 0x4800
	v_add3_u32 v167, s38, v162, v163
	s_setprio 1
	v_add3_u32 v220, s38, v164, v163
	ds_read_b128 v[200:203], v167 offset:0
	ds_read_b128 v[204:207], v220 offset:18432
	ds_read_b128 v[212:215], v167 offset:4608
	ds_read_b128 v[208:211], v220 offset:23040
	s_waitcnt lgkmcnt(2)
	v_mfma_f32_32x32x16_bf16 v[34:49], v[200:203], v[204:207], v[34:49]
	ds_read_b128 v[216:219], v167 offset:32
	s_waitcnt lgkmcnt(2)
	v_mfma_f32_32x32x16_bf16 v[18:33], v[212:215], v[204:207], v[18:33]
	ds_read_b128 v[204:207], v220 offset:18464
	s_waitcnt lgkmcnt(2)
	v_mfma_f32_32x32x16_bf16 v[2:17], v[200:203], v[208:211], v[2:17]
	ds_read_b128 v[200:203], v167 offset:4640
	v_mfma_f32_32x32x16_bf16 v[50:65], v[212:215], v[208:211], v[50:65]
	ds_read_b128 v[208:211], v220 offset:23072
	s_waitcnt lgkmcnt(2)
	v_mfma_f32_32x32x16_bf16 v[34:49], v[216:219], v[204:207], v[34:49]
	ds_read_b128 v[212:215], v167 offset:64
	s_waitcnt lgkmcnt(2)
	v_mfma_f32_32x32x16_bf16 v[18:33], v[200:203], v[204:207], v[18:33]
	ds_read_b128 v[204:207], v220 offset:18496
	s_waitcnt lgkmcnt(2)
	v_mfma_f32_32x32x16_bf16 v[2:17], v[216:219], v[208:211], v[2:17]
	ds_read_b128 v[216:219], v167 offset:4672
	v_mfma_f32_32x32x16_bf16 v[50:65], v[200:203], v[208:211], v[50:65]
	ds_read_b128 v[208:211], v220 offset:23104
	s_waitcnt lgkmcnt(2)
	v_mfma_f32_32x32x16_bf16 v[34:49], v[212:215], v[204:207], v[34:49]
	ds_read_b128 v[200:203], v167 offset:96
	s_waitcnt lgkmcnt(2)
	v_mfma_f32_32x32x16_bf16 v[18:33], v[216:219], v[204:207], v[18:33]
	ds_read_b128 v[204:207], v220 offset:18528
	s_waitcnt lgkmcnt(2)
	v_mfma_f32_32x32x16_bf16 v[2:17], v[212:215], v[208:211], v[2:17]
	ds_read_b128 v[212:215], v167 offset:4704
	v_mfma_f32_32x32x16_bf16 v[50:65], v[216:219], v[208:211], v[50:65]
	ds_read_b128 v[208:211], v220 offset:23136
	s_waitcnt lgkmcnt(2)
	v_mfma_f32_32x32x16_bf16 v[34:49], v[200:203], v[204:207], v[34:49]
	s_waitcnt lgkmcnt(1)
	v_mfma_f32_32x32x16_bf16 v[18:33], v[212:215], v[204:207], v[18:33]
	s_waitcnt lgkmcnt(0)
	v_mfma_f32_32x32x16_bf16 v[2:17], v[200:203], v[208:211], v[2:17]
	v_mfma_f32_32x32x16_bf16 v[50:65], v[212:215], v[208:211], v[50:65]
	s_add_i32 s37, s37, 2
	s_and_b32 s38, s37, 2
	s_mulk_i32 s38, 0x4800
	s_add_i32 s6, s6, -1
	v_add_u32_e32 v167, s38, v135
	v_lshl_add_u64 v[146:147], v[146:147], 0, s[8:9]
	v_lshl_add_u64 v[148:149], v[148:149], 0, s[8:9]
	v_lshl_add_u64 v[150:151], v[150:151], 0, s[8:9]
	v_lshl_add_u64 v[152:153], v[152:153], 0, s[8:9]
	v_lshl_add_u64 v[154:155], v[154:155], 0, s[8:9]
	v_lshl_add_u64 v[156:157], v[156:157], 0, s[8:9]
	v_lshl_add_u64 v[158:159], v[158:159], 0, s[8:9]
	v_lshl_add_u64 v[160:161], v[160:161], 0, s[8:9]
	s_cmp_lg_u32 s6, 0
	s_waitcnt vmcnt(7)
	ds_write_b128 v167, v[168:171]
	v_lshl_add_u64 v[168:169], v[146:147], 0, v[68:69]
	global_load_dwordx4 v[168:171], v[168:169], off offset:128
	s_waitcnt vmcnt(7)
	ds_write_b128 v167, v[172:175] offset:4608
	v_lshl_add_u64 v[172:173], v[148:149], 0, v[68:69]
	global_load_dwordx4 v[172:175], v[172:173], off offset:128
	s_waitcnt vmcnt(7)
	ds_write_b128 v167, v[176:179] offset:9216
	v_lshl_add_u64 v[176:177], v[150:151], 0, v[68:69]
	global_load_dwordx4 v[176:179], v[176:177], off offset:128
	s_waitcnt vmcnt(7)
	ds_write_b128 v167, v[180:183] offset:13824
	v_lshl_add_u64 v[180:181], v[152:153], 0, v[68:69]
	global_load_dwordx4 v[180:183], v[180:181], off offset:128
	s_waitcnt vmcnt(7)
	ds_write_b128 v167, v[184:187] offset:18432
	v_lshl_add_u64 v[184:185], v[154:155], 0, v[68:69]
	global_load_dwordx4 v[184:187], v[184:185], off offset:128
	s_waitcnt vmcnt(7)
	ds_write_b128 v167, v[188:191] offset:23040
	v_lshl_add_u64 v[188:189], v[156:157], 0, v[68:69]
	global_load_dwordx4 v[188:191], v[188:189], off offset:128
	s_waitcnt vmcnt(7)
	ds_write_b128 v167, v[192:195] offset:27648
	v_lshl_add_u64 v[192:193], v[158:159], 0, v[68:69]
	global_load_dwordx4 v[192:195], v[192:193], off offset:128
	s_waitcnt vmcnt(7)
	ds_write_b128 v167, v[196:199] offset:32256
	v_lshl_add_u64 v[196:197], v[160:161], 0, v[68:69]
	global_load_dwordx4 v[196:199], v[196:197], off offset:128
	s_setprio 0
	s_waitcnt lgkmcnt(0)
	s_barrier
	s_cbranch_scc1 .LBB0_632
	s_and_b32 s38, s37, 2
	s_mulk_i32 s38, 0x4800
	v_add3_u32 v167, s38, v162, v163
	s_setprio 1
	v_add3_u32 v220, s38, v164, v163
	ds_read_b128 v[200:203], v167 offset:0
	ds_read_b128 v[204:207], v220 offset:18432
	ds_read_b128 v[212:215], v167 offset:4608
	ds_read_b128 v[208:211], v220 offset:23040
	s_waitcnt lgkmcnt(2)
	v_mfma_f32_32x32x16_bf16 v[34:49], v[200:203], v[204:207], v[34:49]
	ds_read_b128 v[216:219], v167 offset:32
	s_waitcnt lgkmcnt(2)
	v_mfma_f32_32x32x16_bf16 v[18:33], v[212:215], v[204:207], v[18:33]
	ds_read_b128 v[204:207], v220 offset:18464
	s_waitcnt lgkmcnt(2)
	v_mfma_f32_32x32x16_bf16 v[2:17], v[200:203], v[208:211], v[2:17]
	ds_read_b128 v[200:203], v167 offset:4640
	v_mfma_f32_32x32x16_bf16 v[50:65], v[212:215], v[208:211], v[50:65]
	ds_read_b128 v[208:211], v220 offset:23072
	s_waitcnt lgkmcnt(2)
	v_mfma_f32_32x32x16_bf16 v[34:49], v[216:219], v[204:207], v[34:49]
	ds_read_b128 v[212:215], v167 offset:64
	s_waitcnt lgkmcnt(2)
	v_mfma_f32_32x32x16_bf16 v[18:33], v[200:203], v[204:207], v[18:33]
	ds_read_b128 v[204:207], v220 offset:18496
	s_waitcnt lgkmcnt(2)
	v_mfma_f32_32x32x16_bf16 v[2:17], v[216:219], v[208:211], v[2:17]
	ds_read_b128 v[216:219], v167 offset:4672
	v_mfma_f32_32x32x16_bf16 v[50:65], v[200:203], v[208:211], v[50:65]
	ds_read_b128 v[208:211], v220 offset:23104
	s_waitcnt lgkmcnt(2)
	v_mfma_f32_32x32x16_bf16 v[34:49], v[212:215], v[204:207], v[34:49]
	ds_read_b128 v[200:203], v167 offset:96
	s_waitcnt lgkmcnt(2)
;     ...
;   for (int kt = 0; kt < nk; ++kt) {
;     const int kn = (kt + 1 < nk) ? kt + 1 : kt;
;     GM_LOAD2(kn * 64, kn * bkstep)
;     __builtin_amdgcn_sched_barrier(0);
;     const char* As = smem + (kt & 1) * 2 * TILE_B;
;     const char* Bs = As + TILE_B;
;     if constexpr (HOIST) {
;       bf16x8 fa0[4], fa1[4], fb0[4], fb1[4];
; #pragma unroll
;       for (int st = 0; st < 4; ++st) {
;         fa0[st] = *(const bf16x8*)(As + aoff + st * 32);
;         fb0[st] = *(const bf16x8*)(Bs + boff + st * 32);
;         fa1[st] = *(const bf16x8*)(As + aoff + 32 * LSTR + st * 32);
;         fb1[st] = *(const bf16x8*)(Bs + boff + 32 * LSTR + st * 32);
;       }
;       __builtin_amdgcn_sched_barrier(0);
; #pragma unroll
;       for (int st = 0; st < 4; ++st) {
;         acc[0][0] = mfma32(fa0[st], fb0[st], acc[0][0]);
;         acc[0][1] = mfma32(fa0[st], fb1[st], acc[0][1]);
;         acc[1][0] = mfma32(fa1[st], fb0[st], acc[1][0]);
;         acc[1][1] = mfma32(fa1[st], fb1[st], acc[1][1]);
;       }
;     } else {
; #pragma unroll
;       for (int st = 0; st < 4; ++st) {
;         bf16x8 a0 = *(const bf16x8*)(As + aoff + st * 32);
;         bf16x8 a1 = *(const bf16x8*)(As + aoff + 32 * LSTR + st * 32);
;         bf16x8 b0 = *(const bf16x8*)(Bs + boff + st * 32);
;         bf16x8 b1 = *(const bf16x8*)(Bs + boff + 32 * LSTR + st * 32);
;         acc[0][0] = mfma32(a0, b0, acc[0][0]);
;         acc[0][1] = mfma32(a0, b1, acc[0][1]);
;         acc[1][0] = mfma32(a1, b0, acc[1][0]);
;         acc[1][1] = mfma32(a1, b1, acc[1][1]);
;       }
;     }
;     __builtin_amdgcn_sched_barrier(0);
;     {
;       char* Ad = smem + ((kt + 1) & 1) * 2 * TILE_B;
;       GM_STORE(Ad)
;     }
;     __syncthreads();
;   }
; __device__ __forceinline__ void acc_to_lds(const f32x16 (&acc)[2][2], float* cs) {
;   const int tid = threadIdx.x, lane = tid & 63, wave = tid >> 6;
;   const int wm = wave >> 1, wn = wave & 1;
; #pragma unroll
;   for (int i = 0; i < 2; ++i)
; #pragma unroll
;     for (int j = 0; j < 2; ++j)
; #pragma unroll
;       for (int r = 0; r < 16; ++r) {
;         int row = wm * 64 + i * 32 + (r & 3) + 8 * (r >> 2) + 4 * (lane >> 5);
;         int col = wn * 64 + j * 32 + (lane & 31);
;         cs[row * CSTR + col] = acc[i][j][r];
;       }
;   __syncthreads();
	v_mfma_f32_32x32x16_bf16 v[18:33], v[216:219], v[204:207], v[18:33]
	ds_read_b128 v[204:207], v220 offset:18528
	s_waitcnt lgkmcnt(2)
	v_mfma_f32_32x32x16_bf16 v[2:17], v[212:215], v[208:211], v[2:17]
	ds_read_b128 v[212:215], v167 offset:4704
	v_mfma_f32_32x32x16_bf16 v[50:65], v[216:219], v[208:211], v[50:65]
	ds_read_b128 v[208:211], v220 offset:23136
	s_waitcnt lgkmcnt(2)
	v_mfma_f32_32x32x16_bf16 v[34:49], v[200:203], v[204:207], v[34:49]
	s_waitcnt lgkmcnt(1)
	v_mfma_f32_32x32x16_bf16 v[18:33], v[212:215], v[204:207], v[18:33]
	s_waitcnt lgkmcnt(0)
	v_mfma_f32_32x32x16_bf16 v[2:17], v[200:203], v[208:211], v[2:17]
	v_mfma_f32_32x32x16_bf16 v[50:65], v[212:215], v[208:211], v[50:65]
	s_add_i32 s37, s37, 2
	s_and_b32 s38, s37, 2
	s_mulk_i32 s38, 0x4800
	v_add_u32_e32 v167, s38, v135
	v_lshl_add_u64 v[146:147], v[146:147], 0, s[8:9]
	v_lshl_add_u64 v[148:149], v[148:149], 0, s[8:9]
	v_lshl_add_u64 v[150:151], v[150:151], 0, s[8:9]
	v_lshl_add_u64 v[152:153], v[152:153], 0, s[8:9]
	v_lshl_add_u64 v[154:155], v[154:155], 0, s[8:9]
	v_lshl_add_u64 v[156:157], v[156:157], 0, s[8:9]
	v_lshl_add_u64 v[158:159], v[158:159], 0, s[8:9]
	v_lshl_add_u64 v[160:161], v[160:161], 0, s[8:9]
	s_waitcnt vmcnt(7)
	ds_write_b128 v167, v[168:171]
	s_waitcnt vmcnt(6)
	ds_write_b128 v167, v[172:175] offset:4608
	s_waitcnt vmcnt(5)
	ds_write_b128 v167, v[176:179] offset:9216
	s_waitcnt vmcnt(4)
	ds_write_b128 v167, v[180:183] offset:13824
	s_waitcnt vmcnt(3)
	ds_write_b128 v167, v[184:187] offset:18432
	s_waitcnt vmcnt(2)
	ds_write_b128 v167, v[188:191] offset:23040
	s_waitcnt vmcnt(1)
	ds_write_b128 v167, v[192:195] offset:27648
	s_waitcnt vmcnt(0)
	ds_write_b128 v167, v[196:199] offset:32256
	s_setprio 0
	s_waitcnt lgkmcnt(0)
	s_barrier
	v_lshl_add_u64 v[180:181], v[160:161], 0, v[68:69]
	v_lshl_add_u64 v[176:177], v[158:159], 0, v[68:69]
	v_lshl_add_u64 v[172:173], v[156:157], 0, v[68:69]
	v_lshl_add_u64 v[168:169], v[154:155], 0, v[68:69]
	v_lshl_add_u64 v[158:159], v[152:153], 0, v[68:69]
	v_lshl_add_u64 v[154:155], v[150:151], 0, v[68:69]
	v_lshl_add_u64 v[150:151], v[148:149], 0, v[68:69]
	v_lshl_add_u64 v[146:147], v[146:147], 0, v[68:69]
	s_nop 0
	s_nop 0
	s_nop 0
	s_nop 0
	s_nop 0
	s_nop 0
	s_nop 0
	v_add3_u32 v68, s38, v162, v163
	s_setprio 1
	v_add3_u32 v167, s38, v164, v163
	ds_read_b128 v[184:187], v68 offset:0
	ds_read_b128 v[188:191], v167 offset:18432
	ds_read_b128 v[196:199], v68 offset:4608
	ds_read_b128 v[192:195], v167 offset:23040
	s_waitcnt lgkmcnt(2)
	v_mfma_f32_32x32x16_bf16 v[34:49], v[184:187], v[188:191], v[34:49]
	ds_read_b128 v[200:203], v68 offset:32
	s_waitcnt lgkmcnt(2)
	v_mfma_f32_32x32x16_bf16 v[18:33], v[196:199], v[188:191], v[18:33]
	ds_read_b128 v[188:191], v167 offset:18464
	s_waitcnt lgkmcnt(2)
	v_mfma_f32_32x32x16_bf16 v[2:17], v[184:187], v[192:195], v[2:17]
	ds_read_b128 v[184:187], v68 offset:4640
	v_mfma_f32_32x32x16_bf16 v[50:65], v[196:199], v[192:195], v[50:65]
	ds_read_b128 v[192:195], v167 offset:23072
	s_waitcnt lgkmcnt(2)
	v_mfma_f32_32x32x16_bf16 v[34:49], v[200:203], v[188:191], v[34:49]
	ds_read_b128 v[196:199], v68 offset:64
	s_waitcnt lgkmcnt(2)
	v_mfma_f32_32x32x16_bf16 v[18:33], v[184:187], v[188:191], v[18:33]
	ds_read_b128 v[188:191], v167 offset:18496
	s_waitcnt lgkmcnt(2)
	v_mfma_f32_32x32x16_bf16 v[2:17], v[200:203], v[192:195], v[2:17]
	ds_read_b128 v[200:203], v68 offset:4672
	v_mfma_f32_32x32x16_bf16 v[50:65], v[184:187], v[192:195], v[50:65]
	ds_read_b128 v[192:195], v167 offset:23104
	s_waitcnt lgkmcnt(2)
	v_mfma_f32_32x32x16_bf16 v[34:49], v[196:199], v[188:191], v[34:49]
	ds_read_b128 v[184:187], v68 offset:96
	s_waitcnt lgkmcnt(2)
	v_mfma_f32_32x32x16_bf16 v[18:33], v[200:203], v[188:191], v[18:33]
	ds_read_b128 v[188:191], v167 offset:18528
	s_waitcnt lgkmcnt(2)
	v_mfma_f32_32x32x16_bf16 v[2:17], v[196:199], v[192:195], v[2:17]
	ds_read_b128 v[196:199], v68 offset:4704
	v_mfma_f32_32x32x16_bf16 v[50:65], v[200:203], v[192:195], v[50:65]
	ds_read_b128 v[192:195], v167 offset:23136
	s_waitcnt lgkmcnt(2)
	v_mfma_f32_32x32x16_bf16 v[34:49], v[184:187], v[188:191], v[34:49]
	s_waitcnt lgkmcnt(1)
	v_mfma_f32_32x32x16_bf16 v[18:33], v[196:199], v[188:191], v[18:33]
	s_waitcnt lgkmcnt(0)
	v_mfma_f32_32x32x16_bf16 v[2:17], v[184:187], v[192:195], v[2:17]
	v_mfma_f32_32x32x16_bf16 v[50:65], v[196:199], v[192:195], v[50:65]
	s_setprio 0
	s_waitcnt lgkmcnt(0)
	s_barrier
	ds_write2_b32 v165, v34, v2 offset1:32
	ds_write2_b32 v165, v35, v3 offset0:132 offset1:164
	v_add_u32_e32 v2, 0x400, v165
	ds_write2_b32 v2, v36, v4 offset0:8 offset1:40
	ds_write2_b32 v2, v37, v5 offset0:140 offset1:172
	v_add_u32_e32 v2, 0x1000, v165
	ds_write2_b32 v2, v38, v6 offset0:32 offset1:64
	ds_write2_b32 v2, v39, v7 offset0:164 offset1:196
	v_add_u32_e32 v2, 0x1400, v165
	ds_write2_b32 v2, v40, v8 offset0:40 offset1:72
	ds_write2_b32 v2, v41, v9 offset0:172 offset1:204
	v_add_u32_e32 v2, 0x2000, v165
	ds_write2_b32 v2, v42, v10 offset0:64 offset1:96
	ds_write2_b32 v2, v43, v11 offset0:196 offset1:228
	v_add_u32_e32 v2, 0x2400, v165
	ds_write2_b32 v2, v44, v12 offset0:72 offset1:104
	ds_write2_b32 v2, v45, v13 offset0:204 offset1:236
	v_add_u32_e32 v2, 0x3000, v165
	ds_write2_b32 v2, v46, v14 offset0:96 offset1:128
	v_add_u32_e32 v2, 0x3200, v165
	ds_write2_b32 v2, v47, v15 offset0:100 offset1:132
	v_add_u32_e32 v2, 0x3400, v165
	ds_write2_b32 v2, v48, v16 offset0:104 offset1:136
	v_add_u32_e32 v2, 0x3600, v165
	ds_write2_b32 v2, v49, v17 offset0:108 offset1:140
	v_add_u32_e32 v2, 0x4000, v165
	ds_write2_b32 v2, v18, v50 offset0:128 offset1:160
	v_add_u32_e32 v2, 0x4400, v165
	ds_write2_b32 v2, v19, v51 offset0:4 offset1:36
	ds_write2_b32 v2, v20, v52 offset0:136 offset1:168
	v_add_u32_e32 v2, 0x4800, v165
	ds_write2_b32 v2, v21, v53 offset0:12 offset1:44
	v_add_u32_e32 v2, 0x5000, v165
	ds_write2_b32 v2, v22, v54 offset0:160 offset1:192
	v_add_u32_e32 v2, 0x5400, v165
	ds_write2_b32 v2, v23, v55 offset0:36 offset1:68
	ds_write2_b32 v2, v24, v56 offset0:168 offset1:200
	v_add_u32_e32 v2, 0x5800, v165
	ds_write2_b32 v2, v25, v57 offset0:44 offset1:76
	v_add_u32_e32 v2, 0x6000, v165
	ds_write2_b32 v2, v26, v58 offset0:192 offset1:224
	v_add_u32_e32 v2, 0x6400, v165
	ds_write2_b32 v2, v27, v59 offset0:68 offset1:100
	ds_write2_b32 v2, v28, v60 offset0:200 offset1:232
	v_add_u32_e32 v2, 0x6800, v165
	ds_write2_b32 v2, v29, v61 offset0:76 offset1:108
	v_add_u32_e32 v2, 0x7200, v165
	ds_write2_b32 v2, v30, v62 offset0:96 offset1:128
	v_add_u32_e32 v2, 0x7400, v165
	ds_write2_b32 v2, v31, v63 offset0:100 offset1:132
	v_add_u32_e32 v2, 0x7600, v165
	s_lshl_b32 s6, s36, 11
	ds_write2_b32 v2, v32, v64 offset0:104 offset1:136
	v_add_u32_e32 v2, 0x7800, v165
	v_lshl_add_u64 v[46:47], v[116:117], 0, s[6:7]
	ds_write2_b32 v2, v33, v65 offset0:108 offset1:140
	s_waitcnt lgkmcnt(0)
	s_barrier
; __device__ __forceinline__ void merge_tile(const Params& P, int l, int mt, int nt, char* smem) {
;     ...
;     const u16* gp = WSP(u16, OFF_G) + grow * 3072 + br * 1024 + nt * 128 + half * 64;
; #pragma unroll
;     for (int q = 0; q < 8; ++q) {
;       uint4 gq = *(const uint4*)(gp + q * 8);
;       float4 a = *(const float4*)(cs + r * CSTR + half * 64 + q * 8);
;       float4 c = *(const float4*)(cs + r * CSTR + half * 64 + q * 8 + 4);
;       macc[q * 8 + 0] += __uint_as_float(gq.x << 16) * a.x;
;       macc[q * 8 + 1] += __uint_as_float(gq.x & 0xffff0000u) * a.y;
;       macc[q * 8 + 2] += __uint_as_float(gq.y << 16) * a.z;
;       macc[q * 8 + 3] += __uint_as_float(gq.y & 0xffff0000u) * a.w;
;       macc[q * 8 + 4] += __uint_as_float(gq.z << 16) * c.x;
;       macc[q * 8 + 5] += __uint_as_float(gq.z & 0xffff0000u) * c.y;
;       macc[q * 8 + 6] += __uint_as_float(gq.w << 16) * c.z;
;       macc[q * 8 + 7] += __uint_as_float(gq.w & 0xffff0000u) * c.w;
;     }
;     __syncthreads();
	global_load_dwordx4 v[2:5], v[46:47], off
	global_load_dwordx4 v[6:9], v[46:47], off offset:16
	global_load_dwordx4 v[10:13], v[46:47], off offset:32
	global_load_dwordx4 v[14:17], v[46:47], off offset:48
	global_load_dwordx4 v[18:21], v[46:47], off offset:64
	global_load_dwordx4 v[22:25], v[46:47], off offset:80
	ds_read_b128 v[26:29], v166
	ds_read_b128 v[30:33], v166 offset:16
	ds_read_b128 v[34:37], v166 offset:32
	ds_read_b128 v[38:41], v166 offset:48
	global_load_dwordx4 v[42:45], v[46:47], off offset:112
	s_nop 0
	global_load_dwordx4 v[46:49], v[46:47], off offset:96
	s_add_i32 s36, s36, 1
	s_cmp_lg_u32 s36, 3
	s_waitcnt vmcnt(7)
	v_lshlrev_b32_e32 v50, 16, v2
	v_and_b32_e32 v51, 0xffff0000, v2
	v_lshlrev_b32_e32 v2, 16, v3
	v_and_b32_e32 v3, 0xffff0000, v3
	s_waitcnt lgkmcnt(3)
	v_pk_fma_f32 v[142:143], v[28:29], v[2:3], v[142:143]
	v_lshlrev_b32_e32 v2, 16, v4
	v_and_b32_e32 v3, 0xffff0000, v4
	s_waitcnt lgkmcnt(2)
	v_pk_fma_f32 v[140:141], v[30:31], v[2:3], v[140:141]
	v_lshlrev_b32_e32 v2, 16, v5
	v_and_b32_e32 v3, 0xffff0000, v5
	v_pk_fma_f32 v[138:139], v[32:33], v[2:3], v[138:139]
	s_waitcnt vmcnt(6)
	v_lshlrev_b32_e32 v2, 16, v6
	v_and_b32_e32 v3, 0xffff0000, v6
	s_waitcnt lgkmcnt(1)
	v_pk_fma_f32 v[136:137], v[34:35], v[2:3], v[136:137]
	v_lshlrev_b32_e32 v2, 16, v7
	v_and_b32_e32 v3, 0xffff0000, v7
	v_pk_fma_f32 v[132:133], v[36:37], v[2:3], v[132:133]
	v_lshlrev_b32_e32 v2, 16, v8
	v_and_b32_e32 v3, 0xffff0000, v8
	s_waitcnt lgkmcnt(0)
	v_pk_fma_f32 v[130:131], v[38:39], v[2:3], v[130:131]
	ds_read_b128 v[2:5], v166 offset:64
	v_lshlrev_b32_e32 v6, 16, v9
	v_and_b32_e32 v7, 0xffff0000, v9
	v_pk_fma_f32 v[128:129], v[40:41], v[6:7], v[128:129]
	ds_read_b128 v[6:9], v166 offset:80
	v_pk_fma_f32 v[144:145], v[26:27], v[50:51], v[144:145]
	s_waitcnt vmcnt(5)
	v_lshlrev_b32_e32 v26, 16, v10
	v_and_b32_e32 v27, 0xffff0000, v10
	s_waitcnt lgkmcnt(1)
	v_pk_fma_f32 v[126:127], v[2:3], v[26:27], v[126:127]
	v_lshlrev_b32_e32 v2, 16, v11
	v_and_b32_e32 v3, 0xffff0000, v11
	v_pk_fma_f32 v[124:125], v[4:5], v[2:3], v[124:125]
	v_lshlrev_b32_e32 v2, 16, v12
	v_and_b32_e32 v3, 0xffff0000, v12
	s_waitcnt lgkmcnt(0)
	v_pk_fma_f32 v[122:123], v[6:7], v[2:3], v[122:123]
	ds_read_b128 v[2:5], v166 offset:96
	v_lshlrev_b32_e32 v6, 16, v13
	v_and_b32_e32 v7, 0xffff0000, v13
	v_pk_fma_f32 v[120:121], v[8:9], v[6:7], v[120:121]
	ds_read_b128 v[6:9], v166 offset:112
	s_waitcnt vmcnt(4)
	v_lshlrev_b32_e32 v10, 16, v14
	v_and_b32_e32 v11, 0xffff0000, v14
	s_waitcnt lgkmcnt(1)
	v_pk_fma_f32 v[118:119], v[2:3], v[10:11], v[118:119]
	v_lshlrev_b32_e32 v2, 16, v15
	v_and_b32_e32 v3, 0xffff0000, v15
	v_pk_fma_f32 v[114:115], v[4:5], v[2:3], v[114:115]
	v_lshlrev_b32_e32 v2, 16, v16
	v_and_b32_e32 v3, 0xffff0000, v16
	s_waitcnt lgkmcnt(0)
	v_pk_fma_f32 v[112:113], v[6:7], v[2:3], v[112:113]
	ds_read_b128 v[2:5], v166 offset:128
	v_lshlrev_b32_e32 v6, 16, v17
	v_and_b32_e32 v7, 0xffff0000, v17
	v_pk_fma_f32 v[110:111], v[8:9], v[6:7], v[110:111]
	ds_read_b128 v[6:9], v166 offset:144
	s_waitcnt vmcnt(3)
	v_lshlrev_b32_e32 v10, 16, v18
	v_and_b32_e32 v11, 0xffff0000, v18
	s_waitcnt lgkmcnt(1)
	v_pk_fma_f32 v[106:107], v[2:3], v[10:11], v[106:107]
	v_lshlrev_b32_e32 v2, 16, v19
	v_and_b32_e32 v3, 0xffff0000, v19
	v_pk_fma_f32 v[104:105], v[4:5], v[2:3], v[104:105]
	v_lshlrev_b32_e32 v2, 16, v20
	v_and_b32_e32 v3, 0xffff0000, v20
	s_waitcnt lgkmcnt(0)
	v_pk_fma_f32 v[102:103], v[6:7], v[2:3], v[102:103]
	ds_read_b128 v[2:5], v166 offset:160
	v_lshlrev_b32_e32 v6, 16, v21
	v_and_b32_e32 v7, 0xffff0000, v21
	v_pk_fma_f32 v[100:101], v[8:9], v[6:7], v[100:101]
	ds_read_b128 v[6:9], v166 offset:176
	s_waitcnt vmcnt(2)
	v_lshlrev_b32_e32 v10, 16, v22
	v_and_b32_e32 v11, 0xffff0000, v22
	s_waitcnt lgkmcnt(1)
	v_pk_fma_f32 v[98:99], v[2:3], v[10:11], v[98:99]
	v_lshlrev_b32_e32 v2, 16, v23
	v_and_b32_e32 v3, 0xffff0000, v23
	v_pk_fma_f32 v[96:97], v[4:5], v[2:3], v[96:97]
	v_lshlrev_b32_e32 v2, 16, v24
	v_and_b32_e32 v3, 0xffff0000, v24
	s_waitcnt lgkmcnt(0)
	v_pk_fma_f32 v[94:95], v[6:7], v[2:3], v[94:95]
	ds_read_b128 v[2:5], v166 offset:192
	v_lshlrev_b32_e32 v6, 16, v25
	v_and_b32_e32 v7, 0xffff0000, v25
	v_pk_fma_f32 v[92:93], v[8:9], v[6:7], v[92:93]
	ds_read_b128 v[6:9], v166 offset:208
	s_waitcnt vmcnt(0)
	v_lshlrev_b32_e32 v10, 16, v46
	v_and_b32_e32 v11, 0xffff0000, v46
	s_waitcnt lgkmcnt(1)
	v_pk_fma_f32 v[90:91], v[2:3], v[10:11], v[90:91]
	v_lshlrev_b32_e32 v2, 16, v47
	v_and_b32_e32 v3, 0xffff0000, v47
	v_pk_fma_f32 v[88:89], v[4:5], v[2:3], v[88:89]
	v_lshlrev_b32_e32 v2, 16, v48
	v_and_b32_e32 v3, 0xffff0000, v48
	s_waitcnt lgkmcnt(0)
	v_pk_fma_f32 v[86:87], v[6:7], v[2:3], v[86:87]
	ds_read_b128 v[2:5], v166 offset:224
	v_lshlrev_b32_e32 v6, 16, v49
	v_and_b32_e32 v7, 0xffff0000, v49
	v_pk_fma_f32 v[84:85], v[8:9], v[6:7], v[84:85]
	ds_read_b128 v[6:9], v166 offset:240
	v_lshlrev_b32_e32 v10, 16, v42
	v_and_b32_e32 v11, 0xffff0000, v42
	s_waitcnt lgkmcnt(1)
	v_pk_fma_f32 v[82:83], v[2:3], v[10:11], v[82:83]
	v_lshlrev_b32_e32 v2, 16, v43
	v_and_b32_e32 v3, 0xffff0000, v43
	v_pk_fma_f32 v[80:81], v[4:5], v[2:3], v[80:81]
	v_lshlrev_b32_e32 v2, 16, v44
	v_and_b32_e32 v3, 0xffff0000, v44
	s_waitcnt lgkmcnt(0)
	v_pk_fma_f32 v[78:79], v[6:7], v[2:3], v[78:79]
	v_lshlrev_b32_e32 v2, 16, v45
	v_and_b32_e32 v3, 0xffff0000, v45
	v_pk_fma_f32 v[76:77], v[8:9], v[2:3], v[76:77]
	s_barrier
; __device__ __forceinline__ void store_row64_bf16(const float* v, u16* dst) {
; #pragma unroll
;   for (int q = 0; q < 8; ++q) {
;     uint4 o;
;     o.x = pack2(v[q * 8 + 0], v[q * 8 + 1]);
;     o.y = pack2(v[q * 8 + 2], v[q * 8 + 3]);
;     o.z = pack2(v[q * 8 + 4], v[q * 8 + 5]);
;     o.w = pack2(v[q * 8 + 6], v[q * 8 + 7]);
;     *(uint4*)(dst + q * 8) = o;
;   }
; }
; __device__ __forceinline__ void merge_tile(const Params& P, int l, int mt, int nt, char* smem) {
;     ...
;     __syncthreads();
;   }
;   store_row64_bf16(macc, WSP(u16, OFF_M) + grow * DM + nt * 128 + half * 64);
	s_cbranch_scc1 .LBB0_631
	v_lshlrev_b64 v[2:3], 11, v[108:109]
	v_lshl_add_u64 v[2:3], s[4:5], 0, v[2:3]
	v_lshl_add_u64 v[2:3], s[12:13], 1, v[2:3]
	v_mov_b32_e32 v75, v69
	v_lshl_add_u64 v[6:7], v[2:3], 0, v[74:75]
	v_cvt_pk_bf16_f32 v2, v144, v145
	v_cvt_pk_bf16_f32 v3, v142, v143
	v_cvt_pk_bf16_f32 v4, v140, v141
	v_cvt_pk_bf16_f32 v5, v138, v139
	global_store_dwordx4 v[6:7], v[2:5], off
	v_readlane_b32 s40, v253, 37
	v_readlane_b32 s48, v253, 45
	v_cvt_pk_bf16_f32 v2, v136, v137
	v_cvt_pk_bf16_f32 v3, v132, v133
	v_cvt_pk_bf16_f32 v4, v130, v131
	v_cvt_pk_bf16_f32 v5, v128, v129
	global_store_dwordx4 v[6:7], v[2:5], off offset:16
	v_readlane_b32 s49, v253, 46
	v_readlane_b32 s50, v253, 47
	v_cvt_pk_bf16_f32 v2, v126, v127
	v_cvt_pk_bf16_f32 v3, v124, v125
	v_cvt_pk_bf16_f32 v4, v122, v123
	v_cvt_pk_bf16_f32 v5, v120, v121
	global_store_dwordx4 v[6:7], v[2:5], off offset:32
	v_readlane_b32 s51, v253, 48
	v_readlane_b32 s52, v253, 49
	v_cvt_pk_bf16_f32 v2, v118, v119
	v_cvt_pk_bf16_f32 v3, v114, v115
	v_cvt_pk_bf16_f32 v4, v112, v113
	v_cvt_pk_bf16_f32 v5, v110, v111
	global_store_dwordx4 v[6:7], v[2:5], off offset:48
	v_readlane_b32 s53, v253, 50
	v_readlane_b32 s54, v253, 51
	v_cvt_pk_bf16_f32 v2, v106, v107
	v_cvt_pk_bf16_f32 v3, v104, v105
	v_cvt_pk_bf16_f32 v4, v102, v103
	v_cvt_pk_bf16_f32 v5, v100, v101
	global_store_dwordx4 v[6:7], v[2:5], off offset:64
	v_readlane_b32 s55, v253, 52
	v_readlane_b32 s41, v253, 38
	v_cvt_pk_bf16_f32 v2, v98, v99
	v_cvt_pk_bf16_f32 v3, v96, v97
	v_cvt_pk_bf16_f32 v4, v94, v95
	v_cvt_pk_bf16_f32 v5, v92, v93
	global_store_dwordx4 v[6:7], v[2:5], off offset:80
	v_readlane_b32 s42, v253, 39
	v_readlane_b32 s43, v253, 40
	v_cvt_pk_bf16_f32 v2, v90, v91
	v_cvt_pk_bf16_f32 v3, v88, v89
	v_cvt_pk_bf16_f32 v4, v86, v87
	v_cvt_pk_bf16_f32 v5, v84, v85
	global_store_dwordx4 v[6:7], v[2:5], off offset:96
	v_readlane_b32 s44, v253, 41
	v_readlane_b32 s45, v253, 42
	v_cvt_pk_bf16_f32 v2, v82, v83
	v_cvt_pk_bf16_f32 v3, v80, v81
	v_cvt_pk_bf16_f32 v4, v78, v79
	v_cvt_pk_bf16_f32 v5, v76, v77
	global_store_dwordx4 v[6:7], v[2:5], off offset:112
	v_readlane_b32 s46, v253, 43
	v_readlane_b32 s47, v253, 44
	s_branch .LBB0_628

;     ...
;   for (int kt = 0; kt < nk; ++kt) {
;     const int kn = (kt + 1 < nk) ? kt + 1 : kt;
;     GM_LOAD2(kn * 64, kn * bkstep)
;     __builtin_amdgcn_sched_barrier(0);
;     const char* As = smem + (kt & 1) * 2 * TILE_B;
;     const char* Bs = As + TILE_B;
;     if constexpr (HOIST) {
;       bf16x8 fa0[4], fa1[4], fb0[4], fb1[4];
; #pragma unroll
;       for (int st = 0; st < 4; ++st) {
;         fa0[st] = *(const bf16x8*)(As + aoff + st * 32);
;         fb0[st] = *(const bf16x8*)(Bs + boff + st * 32);
;         fa1[st] = *(const bf16x8*)(As + aoff + 32 * LSTR + st * 32);
;         fb1[st] = *(const bf16x8*)(Bs + boff + 32 * LSTR + st * 32);
;       }
;       __builtin_amdgcn_sched_barrier(0);
; #pragma unroll
;       for (int st = 0; st < 4; ++st) {
;         acc[0][0] = mfma32(fa0[st], fb0[st], acc[0][0]);
;         acc[0][1] = mfma32(fa0[st], fb1[st], acc[0][1]);
;         acc[1][0] = mfma32(fa1[st], fb0[st], acc[1][0]);
;         acc[1][1] = mfma32(fa1[st], fb1[st], acc[1][1]);
;       }
;     } else {
; #pragma unroll
;       for (int st = 0; st < 4; ++st) {
;         bf16x8 a0 = *(const bf16x8*)(As + aoff + st * 32);
;         bf16x8 a1 = *(const bf16x8*)(As + aoff + 32 * LSTR + st * 32);
;         bf16x8 b0 = *(const bf16x8*)(Bs + boff + st * 32);
;         bf16x8 b1 = *(const bf16x8*)(Bs + boff + 32 * LSTR + st * 32);
;         acc[0][0] = mfma32(a0, b0, acc[0][0]);
;         acc[0][1] = mfma32(a0, b1, acc[0][1]);
;         acc[1][0] = mfma32(a1, b0, acc[1][0]);
;         acc[1][1] = mfma32(a1, b1, acc[1][1]);
;       }
;     }
;     __builtin_amdgcn_sched_barrier(0);
;     {
;       char* Ad = smem + ((kt + 1) & 1) * 2 * TILE_B;
;       GM_STORE(Ad)
;     }
;     __syncthreads();
;   }
.LBB0_722:
	s_and_b32 s18, s2, 2
	s_mulk_i32 s18, 0x4800
	v_add3_u32 v66, s18, v90, v91
	v_add3_u32 v95, s18, v92, v91
	s_setprio 1
	ds_read_b128 v[128:131], v66 offset:0
	ds_read_b128 v[136:139], v95 offset:18432
	ds_read_b128 v[144:147], v66 offset:4608
	ds_read_b128 v[140:143], v95 offset:23040
	s_waitcnt lgkmcnt(2)
	v_mfma_f32_32x32x16_bf16 v[50:65], v[128:131], v[136:139], v[50:65]
	ds_read_b128 v[148:151], v66 offset:32
	s_waitcnt lgkmcnt(2)
	v_mfma_f32_32x32x16_bf16 v[18:33], v[144:147], v[136:139], v[18:33]
	ds_read_b128 v[136:139], v95 offset:18464
	s_waitcnt lgkmcnt(2)
	v_mfma_f32_32x32x16_bf16 v[34:49], v[128:131], v[140:143], v[34:49]
	ds_read_b128 v[128:131], v66 offset:4640
	v_mfma_f32_32x32x16_bf16 v[2:17], v[144:147], v[140:143], v[2:17]
	ds_read_b128 v[140:143], v95 offset:23072
	s_waitcnt lgkmcnt(2)
	v_mfma_f32_32x32x16_bf16 v[50:65], v[148:151], v[136:139], v[50:65]
	ds_read_b128 v[144:147], v66 offset:64
	s_waitcnt lgkmcnt(2)
	v_mfma_f32_32x32x16_bf16 v[18:33], v[128:131], v[136:139], v[18:33]
	ds_read_b128 v[136:139], v95 offset:18496
	s_waitcnt lgkmcnt(2)
	v_mfma_f32_32x32x16_bf16 v[34:49], v[148:151], v[140:143], v[34:49]
	ds_read_b128 v[148:151], v66 offset:4672
	v_mfma_f32_32x32x16_bf16 v[2:17], v[128:131], v[140:143], v[2:17]
	ds_read_b128 v[140:143], v95 offset:23104
	s_waitcnt lgkmcnt(2)
	v_mfma_f32_32x32x16_bf16 v[50:65], v[144:147], v[136:139], v[50:65]
	ds_read_b128 v[128:131], v66 offset:96
	s_waitcnt lgkmcnt(2)
	v_mfma_f32_32x32x16_bf16 v[18:33], v[148:151], v[136:139], v[18:33]
	ds_read_b128 v[136:139], v95 offset:18528
	s_waitcnt lgkmcnt(2)
	v_mfma_f32_32x32x16_bf16 v[34:49], v[144:147], v[140:143], v[34:49]
	ds_read_b128 v[144:147], v66 offset:4704
	v_mfma_f32_32x32x16_bf16 v[2:17], v[148:151], v[140:143], v[2:17]
	ds_read_b128 v[140:143], v95 offset:23136
	s_waitcnt lgkmcnt(2)
	v_mfma_f32_32x32x16_bf16 v[50:65], v[128:131], v[136:139], v[50:65]
	s_waitcnt lgkmcnt(1)
	v_mfma_f32_32x32x16_bf16 v[18:33], v[144:147], v[136:139], v[18:33]
	s_waitcnt lgkmcnt(0)
	v_mfma_f32_32x32x16_bf16 v[34:49], v[128:131], v[140:143], v[34:49]
	v_mfma_f32_32x32x16_bf16 v[2:17], v[144:147], v[140:143], v[2:17]
	s_add_i32 s2, s2, 2
	s_and_b32 s18, s2, 2
	s_add_u32 s16, s16, 0x80
	s_mulk_i32 s18, 0x4800
	s_addc_u32 s17, s17, 0
	v_add_u32_e32 v66, s18, v1
	s_cmpk_lg_i32 s16, 0x700
	s_waitcnt vmcnt(7)
	ds_write_b128 v66, v[96:99]
	v_lshl_add_u64 v[96:97], v[88:89], 0, s[16:17]
	v_add_co_u32_e32 v96, vcc, s24, v96
	s_nop 1
	v_addc_co_u32_e32 v97, vcc, 0, v97, vcc
	global_load_dwordx4 v[96:99], v[96:97], off offset:384
	s_waitcnt vmcnt(7)
	ds_write_b128 v66, v[100:103] offset:4608
	v_lshl_add_u64 v[100:101], v[88:89], 0, s[16:17]
	v_add_co_u32_e32 v100, vcc, s25, v100
	s_nop 1
	v_addc_co_u32_e32 v101, vcc, 0, v101, vcc
	global_load_dwordx4 v[100:103], v[100:101], off offset:384
	s_waitcnt vmcnt(7)
	ds_write_b128 v66, v[104:107] offset:9216
	v_lshl_add_u64 v[104:105], v[88:89], 0, s[16:17]
	v_add_co_u32_e32 v104, vcc, s26, v104
	s_nop 1
	v_addc_co_u32_e32 v105, vcc, 0, v105, vcc
	global_load_dwordx4 v[104:107], v[104:105], off offset:384
	s_waitcnt vmcnt(7)
	ds_write_b128 v66, v[108:111] offset:13824
	v_lshl_add_u64 v[108:109], v[88:89], 0, s[16:17]
	v_add_co_u32_e32 v108, vcc, s27, v108
	s_nop 1
	v_addc_co_u32_e32 v109, vcc, 0, v109, vcc
	global_load_dwordx4 v[108:111], v[108:109], off offset:384
	s_waitcnt vmcnt(7)
	ds_write_b128 v66, v[112:115] offset:18432
	v_lshl_add_u64 v[112:113], v[78:79], 0, s[16:17]
	v_add_co_u32_e32 v112, vcc, s28, v112
	s_nop 1
	v_addc_co_u32_e32 v113, vcc, 0, v113, vcc
	global_load_dwordx4 v[112:115], v[112:113], off offset:128
	s_waitcnt vmcnt(7)
	ds_write_b128 v66, v[116:119] offset:23040
	v_lshl_add_u64 v[116:117], v[78:79], 0, s[16:17]
	v_add_co_u32_e32 v116, vcc, s29, v116
	s_nop 1
	v_addc_co_u32_e32 v117, vcc, 0, v117, vcc
	global_load_dwordx4 v[116:119], v[116:117], off offset:128
	s_waitcnt vmcnt(7)
	ds_write_b128 v66, v[120:123] offset:27648
	v_lshl_add_u64 v[120:121], v[78:79], 0, s[16:17]
	v_add_co_u32_e32 v120, vcc, s30, v120
	s_nop 1
	v_addc_co_u32_e32 v121, vcc, 0, v121, vcc
	global_load_dwordx4 v[120:123], v[120:121], off offset:128
	s_waitcnt vmcnt(7)
	ds_write_b128 v66, v[124:127] offset:32256
	v_lshl_add_u64 v[124:125], v[78:79], 0, s[16:17]
	v_add_co_u32_e32 v124, vcc, s31, v124
	s_nop 1
	v_addc_co_u32_e32 v125, vcc, 0, v125, vcc
	global_load_dwordx4 v[124:127], v[124:125], off offset:128
	s_setprio 0
	s_waitcnt lgkmcnt(0)
	s_barrier
	s_cbranch_scc1 .LBB0_722
;     ...
;   for (int kt = 0; kt < nk; ++kt) {
;     const int kn = (kt + 1 < nk) ? kt + 1 : kt;
;     GM_LOAD2(kn * 64, kn * bkstep)
;     __builtin_amdgcn_sched_barrier(0);
;     const char* As = smem + (kt & 1) * 2 * TILE_B;
;     const char* Bs = As + TILE_B;
;     if constexpr (HOIST) {
;       bf16x8 fa0[4], fa1[4], fb0[4], fb1[4];
; #pragma unroll
;       for (int st = 0; st < 4; ++st) {
;         fa0[st] = *(const bf16x8*)(As + aoff + st * 32);
;         fb0[st] = *(const bf16x8*)(Bs + boff + st * 32);
;         fa1[st] = *(const bf16x8*)(As + aoff + 32 * LSTR + st * 32);
;         fb1[st] = *(const bf16x8*)(Bs + boff + 32 * LSTR + st * 32);
;       }
;       __builtin_amdgcn_sched_barrier(0);
; #pragma unroll
;       for (int st = 0; st < 4; ++st) {
;         acc[0][0] = mfma32(fa0[st], fb0[st], acc[0][0]);
;         acc[0][1] = mfma32(fa0[st], fb1[st], acc[0][1]);
;         acc[1][0] = mfma32(fa1[st], fb0[st], acc[1][0]);
;         acc[1][1] = mfma32(fa1[st], fb1[st], acc[1][1]);
;       }
;     } else {
; #pragma unroll
;       for (int st = 0; st < 4; ++st) {
;         bf16x8 a0 = *(const bf16x8*)(As + aoff + st * 32);
;         bf16x8 a1 = *(const bf16x8*)(As + aoff + 32 * LSTR + st * 32);
;         bf16x8 b0 = *(const bf16x8*)(Bs + boff + st * 32);
;         bf16x8 b1 = *(const bf16x8*)(Bs + boff + 32 * LSTR + st * 32);
;         acc[0][0] = mfma32(a0, b0, acc[0][0]);
;         acc[0][1] = mfma32(a0, b1, acc[0][1]);
;         acc[1][0] = mfma32(a1, b0, acc[1][0]);
;         acc[1][1] = mfma32(a1, b1, acc[1][1]);
;       }
;     }
;     __builtin_amdgcn_sched_barrier(0);
;     {
;       char* Ad = smem + ((kt + 1) & 1) * 2 * TILE_B;
;       GM_STORE(Ad)
;     }
;     __syncthreads();
;   }
	s_and_b32 s18, s2, 2
	s_mulk_i32 s18, 0x4800
	v_add3_u32 v66, s18, v90, v91
	v_add3_u32 v95, s18, v92, v91
	s_setprio 1
	ds_read_b128 v[128:131], v66 offset:0
	ds_read_b128 v[136:139], v95 offset:18432
	ds_read_b128 v[144:147], v66 offset:4608
	ds_read_b128 v[140:143], v95 offset:23040
	s_waitcnt lgkmcnt(2)
	v_mfma_f32_32x32x16_bf16 v[50:65], v[128:131], v[136:139], v[50:65]
	ds_read_b128 v[148:151], v66 offset:32
	s_waitcnt lgkmcnt(2)
	v_mfma_f32_32x32x16_bf16 v[18:33], v[144:147], v[136:139], v[18:33]
	ds_read_b128 v[136:139], v95 offset:18464
	s_waitcnt lgkmcnt(2)
	v_mfma_f32_32x32x16_bf16 v[34:49], v[128:131], v[140:143], v[34:49]
	ds_read_b128 v[128:131], v66 offset:4640
	v_mfma_f32_32x32x16_bf16 v[2:17], v[144:147], v[140:143], v[2:17]
	ds_read_b128 v[140:143], v95 offset:23072
	s_waitcnt lgkmcnt(2)
	v_mfma_f32_32x32x16_bf16 v[50:65], v[148:151], v[136:139], v[50:65]
	ds_read_b128 v[144:147], v66 offset:64
	s_waitcnt lgkmcnt(2)
	v_mfma_f32_32x32x16_bf16 v[18:33], v[128:131], v[136:139], v[18:33]
	ds_read_b128 v[136:139], v95 offset:18496
	s_waitcnt lgkmcnt(2)
	v_mfma_f32_32x32x16_bf16 v[34:49], v[148:151], v[140:143], v[34:49]
	ds_read_b128 v[148:151], v66 offset:4672
	v_mfma_f32_32x32x16_bf16 v[2:17], v[128:131], v[140:143], v[2:17]
	ds_read_b128 v[140:143], v95 offset:23104
	s_waitcnt lgkmcnt(2)
	v_mfma_f32_32x32x16_bf16 v[50:65], v[144:147], v[136:139], v[50:65]
	ds_read_b128 v[128:131], v66 offset:96
	s_waitcnt lgkmcnt(2)
	v_mfma_f32_32x32x16_bf16 v[18:33], v[148:151], v[136:139], v[18:33]
	ds_read_b128 v[136:139], v95 offset:18528
	s_waitcnt lgkmcnt(2)
	v_mfma_f32_32x32x16_bf16 v[34:49], v[144:147], v[140:143], v[34:49]
	ds_read_b128 v[144:147], v66 offset:4704
	v_mfma_f32_32x32x16_bf16 v[2:17], v[148:151], v[140:143], v[2:17]
	ds_read_b128 v[140:143], v95 offset:23136
	s_waitcnt lgkmcnt(2)
	v_mfma_f32_32x32x16_bf16 v[50:65], v[128:131], v[136:139], v[50:65]
	s_waitcnt lgkmcnt(1)
	v_mfma_f32_32x32x16_bf16 v[18:33], v[144:147], v[136:139], v[18:33]
	s_waitcnt lgkmcnt(0)
	v_mfma_f32_32x32x16_bf16 v[34:49], v[128:131], v[140:143], v[34:49]
	v_mfma_f32_32x32x16_bf16 v[2:17], v[144:147], v[140:143], v[2:17]
	s_add_i32 s2, s2, 2
	s_and_b32 s18, s2, 2
	s_add_u32 s16, s16, 0x80
	s_mulk_i32 s18, 0x4800
	s_addc_u32 s17, s17, 0
	v_add_u32_e32 v66, s18, v1
	s_waitcnt vmcnt(7)
	ds_write_b128 v66, v[96:99]
	s_waitcnt vmcnt(6)
	ds_write_b128 v66, v[100:103] offset:4608
	s_waitcnt vmcnt(5)
	ds_write_b128 v66, v[104:107] offset:9216
	s_waitcnt vmcnt(4)
	ds_write_b128 v66, v[108:111] offset:13824
	s_waitcnt vmcnt(3)
	ds_write_b128 v66, v[112:115] offset:18432
	s_waitcnt vmcnt(2)
	ds_write_b128 v66, v[116:119] offset:23040
	s_waitcnt vmcnt(1)
	ds_write_b128 v66, v[120:123] offset:27648
	s_waitcnt vmcnt(0)
	ds_write_b128 v66, v[124:127] offset:32256
	s_setprio 0
	s_waitcnt lgkmcnt(0)
	s_barrier
	v_add_co_u32_e32 v104, vcc, 0x10000, v76
	s_nop 0
	s_nop 0
	s_nop 0
	v_addc_co_u32_e32 v105, vcc, 0, v77, vcc
	v_add_co_u32_e32 v108, vcc, 0x20000, v76
	s_nop 0
	v_addc_co_u32_e32 v109, vcc, 0, v77, vcc
	v_add_co_u32_e32 v76, vcc, 0x30000, v76
	s_lshl_b64 s[14:15], s[14:15], 7
	s_nop 0
	v_addc_co_u32_e32 v77, vcc, 0, v77, vcc
	s_nop 0
	v_add_u32_e32 v66, v90, v91
	v_add_u32_e32 v76, v92, v91
	s_setprio 1
	ds_read_b128 v[116:119], v66 offset:36864
	ds_read_b128 v[120:123], v76 offset:55296
	ds_read_b128 v[128:131], v66 offset:41472
	ds_read_b128 v[124:127], v76 offset:59904
	s_waitcnt lgkmcnt(2)
	v_mfma_f32_32x32x16_bf16 v[50:65], v[116:119], v[120:123], v[50:65]
	ds_read_b128 v[136:139], v66 offset:36896
	s_waitcnt lgkmcnt(2)
	v_mfma_f32_32x32x16_bf16 v[18:33], v[128:131], v[120:123], v[18:33]
	ds_read_b128 v[120:123], v76 offset:55328
	s_waitcnt lgkmcnt(2)
	v_mfma_f32_32x32x16_bf16 v[34:49], v[116:119], v[124:127], v[34:49]
	ds_read_b128 v[116:119], v66 offset:41504
	v_mfma_f32_32x32x16_bf16 v[2:17], v[128:131], v[124:127], v[2:17]
	ds_read_b128 v[124:127], v76 offset:59936
	s_waitcnt lgkmcnt(2)
	v_mfma_f32_32x32x16_bf16 v[50:65], v[136:139], v[120:123], v[50:65]
	ds_read_b128 v[128:131], v66 offset:36928
	s_waitcnt lgkmcnt(2)
	v_mfma_f32_32x32x16_bf16 v[18:33], v[116:119], v[120:123], v[18:33]
	ds_read_b128 v[120:123], v76 offset:55360
	s_waitcnt lgkmcnt(2)
	v_mfma_f32_32x32x16_bf16 v[34:49], v[136:139], v[124:127], v[34:49]
	ds_read_b128 v[136:139], v66 offset:41536
	v_mfma_f32_32x32x16_bf16 v[2:17], v[116:119], v[124:127], v[2:17]
	ds_read_b128 v[124:127], v76 offset:59968
	s_waitcnt lgkmcnt(2)
	v_mfma_f32_32x32x16_bf16 v[50:65], v[128:131], v[120:123], v[50:65]
	ds_read_b128 v[116:119], v66 offset:36960
	s_waitcnt lgkmcnt(2)
	v_mfma_f32_32x32x16_bf16 v[18:33], v[136:139], v[120:123], v[18:33]
	ds_read_b128 v[120:123], v76 offset:55392
	s_waitcnt lgkmcnt(2)
	v_mfma_f32_32x32x16_bf16 v[34:49], v[128:131], v[124:127], v[34:49]
	ds_read_b128 v[128:131], v66 offset:41568
	v_mfma_f32_32x32x16_bf16 v[2:17], v[136:139], v[124:127], v[2:17]
	ds_read_b128 v[124:127], v76 offset:60000
	s_waitcnt lgkmcnt(2)
	v_mfma_f32_32x32x16_bf16 v[50:65], v[116:119], v[120:123], v[50:65]
	s_waitcnt lgkmcnt(1)
	v_mfma_f32_32x32x16_bf16 v[18:33], v[128:131], v[120:123], v[18:33]
	s_waitcnt lgkmcnt(0)
	v_mfma_f32_32x32x16_bf16 v[34:49], v[116:119], v[124:127], v[34:49]
	v_mfma_f32_32x32x16_bf16 v[2:17], v[128:131], v[124:127], v[2:17]
	s_setprio 0
	s_waitcnt lgkmcnt(0)
	s_barrier
; __device__ __forceinline__ void acc_to_lds(const f32x16 (&acc)[2][2], float* cs) {
;   const int tid = threadIdx.x, lane = tid & 63, wave = tid >> 6;
;   const int wm = wave >> 1, wn = wave & 1;
; #pragma unroll
;   for (int i = 0; i < 2; ++i)
; #pragma unroll
;     for (int j = 0; j < 2; ++j)
; #pragma unroll
;       for (int r = 0; r < 16; ++r) {
;         int row = wm * 64 + i * 32 + (r & 3) + 8 * (r >> 2) + 4 * (lane >> 5);
;         int col = wn * 64 + j * 32 + (lane & 31);
;         cs[row * CSTR + col] = acc[i][j][r];
;       }
;   __syncthreads();
; template <bool WIDE>
; __device__ __forceinline__ void outproj_tile(const Params& P, int l, int mt, int nt, char* smem) {
;     ...
;     int tid_ = threadIdx.x;
;     asm volatile("" : "+v"(tid_));
;     const int lane = tid_ & 63, wave = tid_ >> 6;
;     const int r = 32 * wave + (lane & 31), half = lane >> 5;
;     const size_t grow = (size_t)mt * 128 + r;
;     const bool isctx = grow >= NLAT;
;     const int modrow = isctx ? 8 : (int)(grow >> 12);
;     const int col = (nt + hsel) * 128 + half * 64;
;     const float* g1 = WSP(float, OFF_MOD) + ((size_t)l * 9 + modrow) * 6144 + 2048 + col;
;     const float* xin;
;     float* xo;
;     if (!isctx) { xin = (l == 0 ? P.x : P.out) + grow * DM + col; xo = P.out + grow * DM + col; }
;     else { xin = (l == 0 ? P.ctx : WSP(float, OFF_XC)) + (grow - NLAT) * DM + col; xo = WSP(float, OFF_XC) + (grow - NLAT) * DM + col; }
	ds_write2_b32 v93, v50, v34 offset1:32
	ds_write2_b32 v93, v51, v35 offset0:132 offset1:164
	v_add_u32_e32 v34, 0x400, v93
	ds_write2_b32 v34, v52, v36 offset0:8 offset1:40
	ds_write2_b32 v34, v53, v37 offset0:140 offset1:172
	v_add_u32_e32 v34, 0x1000, v93
	ds_write2_b32 v34, v54, v38 offset0:32 offset1:64
	ds_write2_b32 v34, v55, v39 offset0:164 offset1:196
	v_add_u32_e32 v34, 0x1400, v93
	ds_write2_b32 v34, v56, v40 offset0:40 offset1:72
	ds_write2_b32 v34, v57, v41 offset0:172 offset1:204
	v_add_u32_e32 v34, 0x2000, v93
	ds_write2_b32 v34, v58, v42 offset0:64 offset1:96
	ds_write2_b32 v34, v59, v43 offset0:196 offset1:228
	v_add_u32_e32 v34, 0x2400, v93
	ds_write2_b32 v34, v60, v44 offset0:72 offset1:104
	ds_write2_b32 v34, v61, v45 offset0:204 offset1:236
	v_add_u32_e32 v34, 0x3000, v93
	ds_write2_b32 v34, v62, v46 offset0:96 offset1:128
	v_add_u32_e32 v34, 0x3200, v93
	ds_write2_b32 v34, v63, v47 offset0:100 offset1:132
	v_add_u32_e32 v34, 0x3400, v93
	ds_write2_b32 v34, v64, v48 offset0:104 offset1:136
	v_add_u32_e32 v34, 0x3600, v93
	ds_write2_b32 v34, v65, v49 offset0:108 offset1:140
	v_add_u32_e32 v34, 0x4000, v93
	ds_write2_b32 v34, v18, v2 offset0:128 offset1:160
	v_add_u32_e32 v2, 0x4400, v93
	ds_write2_b32 v2, v19, v3 offset0:4 offset1:36
	ds_write2_b32 v2, v20, v4 offset0:136 offset1:168
	v_add_u32_e32 v2, 0x4800, v93
	ds_write2_b32 v2, v21, v5 offset0:12 offset1:44
	v_add_u32_e32 v2, 0x5000, v93
	ds_write2_b32 v2, v22, v6 offset0:160 offset1:192
	v_add_u32_e32 v2, 0x5400, v93
	ds_write2_b32 v2, v23, v7 offset0:36 offset1:68
	ds_write2_b32 v2, v24, v8 offset0:168 offset1:200
	v_add_u32_e32 v2, 0x5800, v93
	ds_write2_b32 v2, v25, v9 offset0:44 offset1:76
	v_add_u32_e32 v2, 0x6000, v93
	ds_write2_b32 v2, v26, v10 offset0:192 offset1:224
	v_add_u32_e32 v2, 0x6400, v93
	ds_write2_b32 v2, v27, v11 offset0:68 offset1:100
	ds_write2_b32 v2, v28, v12 offset0:200 offset1:232
	v_add_u32_e32 v2, 0x6800, v93
	ds_write2_b32 v2, v29, v13 offset0:76 offset1:108
	v_add_u32_e32 v2, 0x7200, v93
	ds_write2_b32 v2, v30, v14 offset0:96 offset1:128
	v_add_u32_e32 v2, 0x7400, v93
	ds_write2_b32 v2, v31, v15 offset0:100 offset1:132
	v_add_u32_e32 v2, 0x7600, v93
	ds_write2_b32 v2, v32, v16 offset0:104 offset1:136
	v_add_u32_e32 v2, 0x7800, v93
	v_mov_b32_e32 v12, v134
	ds_write2_b32 v2, v33, v17 offset0:108 offset1:140
	s_waitcnt lgkmcnt(0)
	s_barrier
	s_nop 0
	v_ashrrev_i32_e32 v2, 1, v12
	v_bfi_b32 v2, s33, v2, v12
	v_ashrrev_i32_e32 v3, 31, v2
	v_lshl_add_u64 v[4:5], s[14:15], 0, v[2:3]
	v_cmp_gt_u64_e32 vcc, s[10:11], v[4:5]
	v_lshlrev_b64 v[10:11], 10, v[4:5]
	s_and_saveexec_b64 s[14:15], vcc
	s_xor_b64 s[14:15], exec, s[14:15]
	s_cbranch_execz .LBB0_725
	v_readlane_b32 s56, v253, 21
	v_lshlrev_b64 v[8:9], 2, v[10:11]
	v_readlane_b32 s57, v253, 22
	v_readlane_b32 s58, v253, 23
	v_readlane_b32 s59, v253, 24
	v_lshl_add_u64 v[6:7], s[56:57], 0, v[8:9]
	v_lshl_add_u64 v[8:9], s[88:89], 0, v[8:9]
	v_readlane_b32 s60, v253, 25
	v_readlane_b32 s61, v253, 26
	v_readlane_b32 s62, v253, 27
	v_readlane_b32 s63, v253, 28
	v_readlane_b32 s64, v253, 29
	v_readlane_b32 s65, v253, 30
	v_readlane_b32 s66, v253, 31
	v_readlane_b32 s67, v253, 32
	v_readlane_b32 s68, v253, 33
	v_readlane_b32 s69, v253, 34
	v_readlane_b32 s70, v253, 35
	v_readlane_b32 s71, v253, 36

;     ...
;   for (int kt = 0; kt < nk; ++kt) {
;     const int kn = (kt + 1 < nk) ? kt + 1 : kt;
;     GM_LOAD2(kn * 64, kn * bkstep)
;     __builtin_amdgcn_sched_barrier(0);
;     const char* As = smem + (kt & 1) * 2 * TILE_B;
;     const char* Bs = As + TILE_B;
;     if constexpr (HOIST) {
;       bf16x8 fa0[4], fa1[4], fb0[4], fb1[4];
; #pragma unroll
;       for (int st = 0; st < 4; ++st) {
;         fa0[st] = *(const bf16x8*)(As + aoff + st * 32);
;         fb0[st] = *(const bf16x8*)(Bs + boff + st * 32);
;         fa1[st] = *(const bf16x8*)(As + aoff + 32 * LSTR + st * 32);
;         fb1[st] = *(const bf16x8*)(Bs + boff + 32 * LSTR + st * 32);
;       }
;       __builtin_amdgcn_sched_barrier(0);
; #pragma unroll
;       for (int st = 0; st < 4; ++st) {
;         acc[0][0] = mfma32(fa0[st], fb0[st], acc[0][0]);
;         acc[0][1] = mfma32(fa0[st], fb1[st], acc[0][1]);
;         acc[1][0] = mfma32(fa1[st], fb0[st], acc[1][0]);
;         acc[1][1] = mfma32(fa1[st], fb1[st], acc[1][1]);
;       }
;     } else {
; #pragma unroll
;       for (int st = 0; st < 4; ++st) {
;         bf16x8 a0 = *(const bf16x8*)(As + aoff + st * 32);
;         bf16x8 a1 = *(const bf16x8*)(As + aoff + 32 * LSTR + st * 32);
;         bf16x8 b0 = *(const bf16x8*)(Bs + boff + st * 32);
;         bf16x8 b1 = *(const bf16x8*)(Bs + boff + 32 * LSTR + st * 32);
;         acc[0][0] = mfma32(a0, b0, acc[0][0]);
;         acc[0][1] = mfma32(a0, b1, acc[0][1]);
;         acc[1][0] = mfma32(a1, b0, acc[1][0]);
;         acc[1][1] = mfma32(a1, b1, acc[1][1]);
;       }
;     }
;     __builtin_amdgcn_sched_barrier(0);
;     {
;       char* Ad = smem + ((kt + 1) & 1) * 2 * TILE_B;
;       GM_STORE(Ad)
;     }
;     __syncthreads();
;   }
.LBB0_1121:
	s_and_b32 s14, s15, 2
	s_mulk_i32 s14, 0x4800
	v_add3_u32 v66, s14, v94, v95
	v_add3_u32 v135, s14, v96, v95
	s_setprio 1
	ds_read_b128 v[130:133], v66 offset:0
	ds_read_b128 v[136:139], v135 offset:18432
	ds_read_b128 v[144:147], v66 offset:4608
	ds_read_b128 v[140:143], v135 offset:23040
	s_waitcnt lgkmcnt(2)
	v_mfma_f32_32x32x16_bf16 v[50:65], v[130:133], v[136:139], v[50:65]
	ds_read_b128 v[148:151], v66 offset:32
	s_waitcnt lgkmcnt(2)
	v_mfma_f32_32x32x16_bf16 v[2:17], v[144:147], v[136:139], v[2:17]
	ds_read_b128 v[136:139], v135 offset:18464
	s_waitcnt lgkmcnt(2)
	v_mfma_f32_32x32x16_bf16 v[18:33], v[130:133], v[140:143], v[18:33]
	ds_read_b128 v[130:133], v66 offset:4640
	v_mfma_f32_32x32x16_bf16 v[34:49], v[144:147], v[140:143], v[34:49]
	ds_read_b128 v[140:143], v135 offset:23072
	s_waitcnt lgkmcnt(2)
	v_mfma_f32_32x32x16_bf16 v[50:65], v[148:151], v[136:139], v[50:65]
	ds_read_b128 v[144:147], v66 offset:64
	s_waitcnt lgkmcnt(2)
	v_mfma_f32_32x32x16_bf16 v[2:17], v[130:133], v[136:139], v[2:17]
	ds_read_b128 v[136:139], v135 offset:18496
	s_waitcnt lgkmcnt(2)
	v_mfma_f32_32x32x16_bf16 v[18:33], v[148:151], v[140:143], v[18:33]
	ds_read_b128 v[148:151], v66 offset:4672
	v_mfma_f32_32x32x16_bf16 v[34:49], v[130:133], v[140:143], v[34:49]
	ds_read_b128 v[140:143], v135 offset:23104
	s_waitcnt lgkmcnt(2)
	v_mfma_f32_32x32x16_bf16 v[50:65], v[144:147], v[136:139], v[50:65]
	ds_read_b128 v[130:133], v66 offset:96
	s_waitcnt lgkmcnt(2)
	v_mfma_f32_32x32x16_bf16 v[2:17], v[148:151], v[136:139], v[2:17]
	ds_read_b128 v[136:139], v135 offset:18528
	s_waitcnt lgkmcnt(2)
	v_mfma_f32_32x32x16_bf16 v[18:33], v[144:147], v[140:143], v[18:33]
	ds_read_b128 v[144:147], v66 offset:4704
	v_mfma_f32_32x32x16_bf16 v[34:49], v[148:151], v[140:143], v[34:49]
	ds_read_b128 v[140:143], v135 offset:23136
	s_waitcnt lgkmcnt(2)
	v_mfma_f32_32x32x16_bf16 v[50:65], v[130:133], v[136:139], v[50:65]
	s_waitcnt lgkmcnt(1)
	v_mfma_f32_32x32x16_bf16 v[2:17], v[144:147], v[136:139], v[2:17]
	s_waitcnt lgkmcnt(0)
	v_mfma_f32_32x32x16_bf16 v[18:33], v[130:133], v[140:143], v[18:33]
	v_mfma_f32_32x32x16_bf16 v[34:49], v[144:147], v[140:143], v[34:49]
	s_add_i32 s15, s15, 2
	s_and_b32 s14, s15, 2
	s_mulk_i32 s14, 0x4800
	v_add_u32_e32 v66, s14, v1
	v_lshl_add_u64 v[90:91], v[90:91], 0, s[4:5]
	v_lshl_add_u64 v[92:93], v[92:93], 0, s[10:11]
	s_cmp_lg_u32 s15, 60
	s_waitcnt vmcnt(7)
	ds_write_b128 v66, v[98:101]
	v_lshl_add_u64 v[98:99], v[92:93], 0, v[68:69]
	v_add_co_u32_e32 v98, vcc, s26, v98
	s_nop 1
	v_addc_co_u32_e32 v99, vcc, 0, v99, vcc
	global_load_dwordx4 v[98:101], v[98:99], off offset:384
	s_waitcnt vmcnt(7)
	ds_write_b128 v66, v[102:105] offset:4608
	v_lshl_add_u64 v[102:103], v[92:93], 0, v[68:69]
	v_add_co_u32_e32 v102, vcc, s27, v102
	s_nop 1
	v_addc_co_u32_e32 v103, vcc, 0, v103, vcc
	global_load_dwordx4 v[102:105], v[102:103], off offset:384
	s_waitcnt vmcnt(7)
	ds_write_b128 v66, v[106:109] offset:9216
	v_lshl_add_u64 v[106:107], v[92:93], 0, v[68:69]
	v_add_co_u32_e32 v106, vcc, s28, v106
	s_nop 1
	v_addc_co_u32_e32 v107, vcc, 0, v107, vcc
	global_load_dwordx4 v[106:109], v[106:107], off offset:384
	s_waitcnt vmcnt(7)
	ds_write_b128 v66, v[110:113] offset:13824
	v_lshl_add_u64 v[110:111], v[92:93], 0, v[68:69]
	v_add_co_u32_e32 v110, vcc, s29, v110
	s_nop 1
	v_addc_co_u32_e32 v111, vcc, 0, v111, vcc
	global_load_dwordx4 v[110:113], v[110:111], off offset:384
	s_waitcnt vmcnt(7)
	ds_write_b128 v66, v[114:117] offset:18432
	v_lshl_add_u64 v[114:115], v[90:91], 0, v[68:69]
	v_add_co_u32_e32 v114, vcc, s30, v114
	s_nop 1
	v_addc_co_u32_e32 v115, vcc, 0, v115, vcc
	global_load_dwordx4 v[114:117], v[114:115], off offset:-4096
	s_waitcnt vmcnt(7)
	ds_write_b128 v66, v[118:121] offset:23040
	v_lshl_add_u64 v[118:119], v[90:91], 0, v[68:69]
	v_add_co_u32_e32 v118, vcc, s30, v118
	s_nop 1
	v_addc_co_u32_e32 v119, vcc, 0, v119, vcc
	global_load_dwordx4 v[118:121], v[118:119], off
	s_waitcnt vmcnt(7)
	ds_write_b128 v66, v[122:125] offset:27648
	v_lshl_add_u64 v[122:123], v[90:91], 0, v[68:69]
	v_add_co_u32_e32 v122, vcc, s31, v122
	s_nop 1
	v_addc_co_u32_e32 v123, vcc, 0, v123, vcc
	global_load_dwordx4 v[122:125], v[122:123], off offset:-4096
	s_waitcnt vmcnt(7)
	ds_write_b128 v66, v[126:129] offset:32256
	v_lshl_add_u64 v[126:127], v[90:91], 0, v[68:69]
	v_add_co_u32_e32 v126, vcc, s31, v126
	s_nop 1
	v_addc_co_u32_e32 v127, vcc, 0, v127, vcc
	global_load_dwordx4 v[126:129], v[126:127], off
	s_setprio 0
	s_waitcnt lgkmcnt(0)
	s_barrier
	s_cbranch_scc1 .LBB0_1121
;     ...
;   for (int kt = 0; kt < nk; ++kt) {
;     const int kn = (kt + 1 < nk) ? kt + 1 : kt;
;     GM_LOAD2(kn * 64, kn * bkstep)
;     __builtin_amdgcn_sched_barrier(0);
;     const char* As = smem + (kt & 1) * 2 * TILE_B;
;     const char* Bs = As + TILE_B;
;     if constexpr (HOIST) {
;       bf16x8 fa0[4], fa1[4], fb0[4], fb1[4];
; #pragma unroll
;       for (int st = 0; st < 4; ++st) {
;         fa0[st] = *(const bf16x8*)(As + aoff + st * 32);
;         fb0[st] = *(const bf16x8*)(Bs + boff + st * 32);
;         fa1[st] = *(const bf16x8*)(As + aoff + 32 * LSTR + st * 32);
;         fb1[st] = *(const bf16x8*)(Bs + boff + 32 * LSTR + st * 32);
;       }
;       __builtin_amdgcn_sched_barrier(0);
; #pragma unroll
;       for (int st = 0; st < 4; ++st) {
;         acc[0][0] = mfma32(fa0[st], fb0[st], acc[0][0]);
;         acc[0][1] = mfma32(fa0[st], fb1[st], acc[0][1]);
;         acc[1][0] = mfma32(fa1[st], fb0[st], acc[1][0]);
;         acc[1][1] = mfma32(fa1[st], fb1[st], acc[1][1]);
;       }
;     } else {
; #pragma unroll
;       for (int st = 0; st < 4; ++st) {
;         bf16x8 a0 = *(const bf16x8*)(As + aoff + st * 32);
;         bf16x8 a1 = *(const bf16x8*)(As + aoff + 32 * LSTR + st * 32);
;         bf16x8 b0 = *(const bf16x8*)(Bs + boff + st * 32);
;         bf16x8 b1 = *(const bf16x8*)(Bs + boff + 32 * LSTR + st * 32);
;         acc[0][0] = mfma32(a0, b0, acc[0][0]);
;         acc[0][1] = mfma32(a0, b1, acc[0][1]);
;         acc[1][0] = mfma32(a1, b0, acc[1][0]);
;         acc[1][1] = mfma32(a1, b1, acc[1][1]);
;       }
;     }
;     __builtin_amdgcn_sched_barrier(0);
;     {
;       char* Ad = smem + ((kt + 1) & 1) * 2 * TILE_B;
;       GM_STORE(Ad)
;     }
;     __syncthreads();
;   }
	s_and_b32 s14, s15, 2
	s_mulk_i32 s14, 0x4800
	v_add3_u32 v66, s14, v94, v95
	v_add3_u32 v135, s14, v96, v95
	s_setprio 1
	ds_read_b128 v[130:133], v66 offset:0
	ds_read_b128 v[136:139], v135 offset:18432
	ds_read_b128 v[144:147], v66 offset:4608
	ds_read_b128 v[140:143], v135 offset:23040
	s_waitcnt lgkmcnt(2)
	v_mfma_f32_32x32x16_bf16 v[50:65], v[130:133], v[136:139], v[50:65]
	ds_read_b128 v[148:151], v66 offset:32
	s_waitcnt lgkmcnt(2)
	v_mfma_f32_32x32x16_bf16 v[2:17], v[144:147], v[136:139], v[2:17]
	ds_read_b128 v[136:139], v135 offset:18464
	s_waitcnt lgkmcnt(2)
	v_mfma_f32_32x32x16_bf16 v[18:33], v[130:133], v[140:143], v[18:33]
	ds_read_b128 v[130:133], v66 offset:4640
	v_mfma_f32_32x32x16_bf16 v[34:49], v[144:147], v[140:143], v[34:49]
	ds_read_b128 v[140:143], v135 offset:23072
	s_waitcnt lgkmcnt(2)
	v_mfma_f32_32x32x16_bf16 v[50:65], v[148:151], v[136:139], v[50:65]
	ds_read_b128 v[144:147], v66 offset:64
	s_waitcnt lgkmcnt(2)
	v_mfma_f32_32x32x16_bf16 v[2:17], v[130:133], v[136:139], v[2:17]
	ds_read_b128 v[136:139], v135 offset:18496
	s_waitcnt lgkmcnt(2)
	v_mfma_f32_32x32x16_bf16 v[18:33], v[148:151], v[140:143], v[18:33]
	ds_read_b128 v[148:151], v66 offset:4672
	v_mfma_f32_32x32x16_bf16 v[34:49], v[130:133], v[140:143], v[34:49]
	ds_read_b128 v[140:143], v135 offset:23104
	s_waitcnt lgkmcnt(2)
	v_mfma_f32_32x32x16_bf16 v[50:65], v[144:147], v[136:139], v[50:65]
	ds_read_b128 v[130:133], v66 offset:96
	s_waitcnt lgkmcnt(2)
	v_mfma_f32_32x32x16_bf16 v[2:17], v[148:151], v[136:139], v[2:17]
	ds_read_b128 v[136:139], v135 offset:18528
	s_waitcnt lgkmcnt(2)
	v_mfma_f32_32x32x16_bf16 v[18:33], v[144:147], v[140:143], v[18:33]
	ds_read_b128 v[144:147], v66 offset:4704
	v_mfma_f32_32x32x16_bf16 v[34:49], v[148:151], v[140:143], v[34:49]
	ds_read_b128 v[140:143], v135 offset:23136
	s_waitcnt lgkmcnt(2)
	v_mfma_f32_32x32x16_bf16 v[50:65], v[130:133], v[136:139], v[50:65]
	s_waitcnt lgkmcnt(1)
	v_mfma_f32_32x32x16_bf16 v[2:17], v[144:147], v[136:139], v[2:17]
	s_waitcnt lgkmcnt(0)
	v_mfma_f32_32x32x16_bf16 v[18:33], v[130:133], v[140:143], v[18:33]
	v_mfma_f32_32x32x16_bf16 v[34:49], v[144:147], v[140:143], v[34:49]
	s_add_i32 s15, s15, 2
	s_and_b32 s14, s15, 2
	s_mulk_i32 s14, 0x4800
	v_add_u32_e32 v66, s14, v1
	v_lshl_add_u64 v[90:91], v[90:91], 0, s[4:5]
	v_lshl_add_u64 v[92:93], v[92:93], 0, s[10:11]
	s_waitcnt vmcnt(7)
	ds_write_b128 v66, v[98:101]
	s_waitcnt vmcnt(6)
	ds_write_b128 v66, v[102:105] offset:4608
	s_waitcnt vmcnt(5)
	ds_write_b128 v66, v[106:109] offset:9216
	s_waitcnt vmcnt(4)
	ds_write_b128 v66, v[110:113] offset:13824
	s_waitcnt vmcnt(3)
	ds_write_b128 v66, v[114:117] offset:18432
	s_waitcnt vmcnt(2)
	ds_write_b128 v66, v[118:121] offset:23040
	s_waitcnt vmcnt(1)
	ds_write_b128 v66, v[122:125] offset:27648
	s_waitcnt vmcnt(0)
	ds_write_b128 v66, v[126:129] offset:32256
	s_setprio 0
	s_waitcnt lgkmcnt(0)
	s_barrier
	v_add_co_u32_e32 v102, vcc, 0x3e0000, v80
	s_nop 0
	s_nop 0
	s_nop 0
	v_addc_co_u32_e32 v103, vcc, 0, v81, vcc
	v_add_co_u32_e32 v106, vcc, 0x3e1000, v80
	s_nop 1
	v_addc_co_u32_e32 v107, vcc, 0, v81, vcc
	v_add_co_u32_e32 v110, vcc, 0x3e2000, v80
	s_nop 0
	v_addc_co_u32_e32 v111, vcc, 0, v81, vcc
	v_add_co_u32_e32 v80, vcc, 0x3e3000, v80
	s_nop 1
	v_addc_co_u32_e32 v81, vcc, 0, v81, vcc
	s_nop 0
	v_add_u32_e32 v66, v94, v95
	v_add_u32_e32 v80, v96, v95
	s_setprio 1
	ds_read_b128 v[118:121], v66 offset:36864
	ds_read_b128 v[122:125], v80 offset:55296
	ds_read_b128 v[130:133], v66 offset:41472
	ds_read_b128 v[126:129], v80 offset:59904
	s_waitcnt lgkmcnt(2)
	v_mfma_f32_32x32x16_bf16 v[50:65], v[118:121], v[122:125], v[50:65]
	ds_read_b128 v[136:139], v66 offset:36896
	s_waitcnt lgkmcnt(2)
	v_mfma_f32_32x32x16_bf16 v[2:17], v[130:133], v[122:125], v[2:17]
	ds_read_b128 v[122:125], v80 offset:55328
	s_waitcnt lgkmcnt(2)
	v_mfma_f32_32x32x16_bf16 v[18:33], v[118:121], v[126:129], v[18:33]
	ds_read_b128 v[118:121], v66 offset:41504
	v_mfma_f32_32x32x16_bf16 v[34:49], v[130:133], v[126:129], v[34:49]
	ds_read_b128 v[126:129], v80 offset:59936
	s_waitcnt lgkmcnt(2)
	v_mfma_f32_32x32x16_bf16 v[50:65], v[136:139], v[122:125], v[50:65]
	ds_read_b128 v[130:133], v66 offset:36928
	s_waitcnt lgkmcnt(2)
	v_mfma_f32_32x32x16_bf16 v[2:17], v[118:121], v[122:125], v[2:17]
	ds_read_b128 v[122:125], v80 offset:55360
	s_waitcnt lgkmcnt(2)
	v_mfma_f32_32x32x16_bf16 v[18:33], v[136:139], v[126:129], v[18:33]
	ds_read_b128 v[136:139], v66 offset:41536
	v_mfma_f32_32x32x16_bf16 v[34:49], v[118:121], v[126:129], v[34:49]
	ds_read_b128 v[126:129], v80 offset:59968
	s_waitcnt lgkmcnt(2)
	v_mfma_f32_32x32x16_bf16 v[50:65], v[130:133], v[122:125], v[50:65]
	ds_read_b128 v[118:121], v66 offset:36960
	s_waitcnt lgkmcnt(2)
	v_mfma_f32_32x32x16_bf16 v[2:17], v[136:139], v[122:125], v[2:17]
	ds_read_b128 v[122:125], v80 offset:55392
	s_waitcnt lgkmcnt(2)
	v_mfma_f32_32x32x16_bf16 v[18:33], v[130:133], v[126:129], v[18:33]
	ds_read_b128 v[130:133], v66 offset:41568
	v_mfma_f32_32x32x16_bf16 v[34:49], v[136:139], v[126:129], v[34:49]
	ds_read_b128 v[126:129], v80 offset:60000
	s_waitcnt lgkmcnt(2)
	v_mfma_f32_32x32x16_bf16 v[50:65], v[118:121], v[122:125], v[50:65]
	s_waitcnt lgkmcnt(1)
	v_mfma_f32_32x32x16_bf16 v[2:17], v[130:133], v[122:125], v[2:17]
	s_waitcnt lgkmcnt(0)
	v_mfma_f32_32x32x16_bf16 v[18:33], v[118:121], v[126:129], v[18:33]
	v_mfma_f32_32x32x16_bf16 v[34:49], v[130:133], v[126:129], v[34:49]
	s_setprio 0
	s_waitcnt lgkmcnt(0)
	s_barrier
; __device__ __forceinline__ void epi_plain(const float* cs, u16* out, size_t ld, size_t row0, int col0) {
;   int tid_ = threadIdx.x;
;   asm volatile("" : "+v"(tid_));
;   const int lane = tid_ & 63, wave = tid_ >> 6;
;   const int r = 32 * wave + (lane & 31), half = lane >> 5;
;   const float* src = cs + r * CSTR + half * 64;
;   u16* dst = out + (row0 + r) * ld + col0 + half * 64;
; #pragma unroll
;   for (int q = 0; q < 8; ++q) {
;     float4 a = *(const float4*)(src + q * 8);
;     float4 b = *(const float4*)(src + q * 8 + 4);
;     uint4 o;
;     o.x = pack2(a.x, a.y); o.y = pack2(a.z, a.w); o.z = pack2(b.x, b.y); o.w = pack2(b.z, b.w);
;     *(uint4*)(dst + q * 8) = o;
;   }
; }
; __device__ __forceinline__ void expert2_tile_narrow(const Params& P, int e, int mt, int nt, char* smem) {
;     ...
;   acc_to_lds(acc, cs);
;   epi_plain(cs, WSP(u16, OFF_YE), DM, (size_t)e * EROWS + mt * 128, nt * 128);
;   __syncthreads();
	ds_write2_b32 v97, v50, v18 offset1:32
	ds_write2_b32 v97, v51, v19 offset0:132 offset1:164
	v_add_u32_e32 v18, 0x400, v97
	ds_write2_b32 v18, v52, v20 offset0:8 offset1:40
	ds_write2_b32 v18, v53, v21 offset0:140 offset1:172
	v_add_u32_e32 v18, 0x1000, v97
	ds_write2_b32 v18, v54, v22 offset0:32 offset1:64
	ds_write2_b32 v18, v55, v23 offset0:164 offset1:196
	v_add_u32_e32 v18, 0x1400, v97
	ds_write2_b32 v18, v56, v24 offset0:40 offset1:72
	ds_write2_b32 v18, v57, v25 offset0:172 offset1:204
	v_add_u32_e32 v18, 0x2000, v97
	ds_write2_b32 v18, v58, v26 offset0:64 offset1:96
	ds_write2_b32 v18, v59, v27 offset0:196 offset1:228
	v_add_u32_e32 v18, 0x2400, v97
	ds_write2_b32 v18, v60, v28 offset0:72 offset1:104
	ds_write2_b32 v18, v61, v29 offset0:204 offset1:236
	v_add_u32_e32 v18, 0x3000, v97
	ds_write2_b32 v18, v62, v30 offset0:96 offset1:128
	v_add_u32_e32 v18, 0x3200, v97
	ds_write2_b32 v18, v63, v31 offset0:100 offset1:132
	v_add_u32_e32 v18, 0x3400, v97
	ds_write2_b32 v18, v64, v32 offset0:104 offset1:136
	v_add_u32_e32 v18, 0x3600, v97
	ds_write2_b32 v18, v65, v33 offset0:108 offset1:140
	v_add_u32_e32 v18, 0x4000, v97
	ds_write2_b32 v18, v2, v34 offset0:128 offset1:160
	v_add_u32_e32 v2, 0x4400, v97
	ds_write2_b32 v2, v3, v35 offset0:4 offset1:36
	ds_write2_b32 v2, v4, v36 offset0:136 offset1:168
	v_add_u32_e32 v2, 0x4800, v97
	ds_write2_b32 v2, v5, v37 offset0:12 offset1:44
	v_add_u32_e32 v2, 0x5000, v97
	ds_write2_b32 v2, v6, v38 offset0:160 offset1:192
	v_add_u32_e32 v2, 0x5400, v97
	ds_write2_b32 v2, v7, v39 offset0:36 offset1:68
	ds_write2_b32 v2, v8, v40 offset0:168 offset1:200
	v_add_u32_e32 v2, 0x5800, v97
	ds_write2_b32 v2, v9, v41 offset0:44 offset1:76
	v_add_u32_e32 v2, 0x6000, v97
	ds_write2_b32 v2, v10, v42 offset0:192 offset1:224
	v_add_u32_e32 v2, 0x6400, v97
	ds_write2_b32 v2, v11, v43 offset0:68 offset1:100
	ds_write2_b32 v2, v12, v44 offset0:200 offset1:232
	v_add_u32_e32 v2, 0x6800, v97
	ds_write2_b32 v2, v13, v45 offset0:76 offset1:108
	v_add_u32_e32 v2, 0x7200, v97
	ds_write2_b32 v2, v14, v46 offset0:96 offset1:128
	v_add_u32_e32 v2, 0x7400, v97
	ds_write2_b32 v2, v15, v47 offset0:100 offset1:132
	v_add_u32_e32 v2, 0x7600, v97
	ds_write2_b32 v2, v16, v48 offset0:104 offset1:136
	v_add_u32_e32 v2, 0x7800, v97
	v_mov_b32_e32 v3, v134
	ds_write2_b32 v2, v17, v49 offset0:108 offset1:140
	s_waitcnt lgkmcnt(0)
	s_barrier
	s_lshl_b32 s2, s2, 8
	v_ashrrev_i32_e32 v2, 1, v3
	v_bfi_b32 v2, s33, v2, v3
	v_lshlrev_b32_e32 v3, 1, v3
	v_and_b32_e32 v5, 64, v3
	v_ashrrev_i32_e32 v3, 31, v2
	v_mul_lo_u32 v4, v2, s16
	v_lshl_add_u64 v[2:3], s[12:13], 0, v[2:3]
	v_lshlrev_b64 v[2:3], 11, v[2:3]
	v_lshl_add_u64 v[2:3], s[0:1], 0, v[2:3]
	v_lshl_add_u32 v20, v5, 2, v4
	v_lshl_add_u64 v[6:7], v[2:3], 0, s[2:3]
	v_lshlrev_b32_e32 v66, 1, v5
	ds_read_b128 v[2:5], v20
	v_lshl_add_u64 v[18:19], v[6:7], 0, v[66:67]
	ds_read_b128 v[6:9], v20 offset:16
	ds_read_b128 v[10:13], v20 offset:32
	ds_read_b128 v[14:17], v20 offset:48
	s_waitcnt lgkmcnt(3)
	v_cvt_pk_bf16_f32 v2, v2, v3
	v_cvt_pk_bf16_f32 v3, v4, v5
	s_waitcnt lgkmcnt(2)
	v_cvt_pk_bf16_f32 v4, v6, v7
	v_cvt_pk_bf16_f32 v5, v8, v9
	global_store_dwordx4 v[18:19], v[2:5], off
	ds_read_b128 v[6:9], v20 offset:64
	s_add_i32 s35, s35, s94
	s_waitcnt lgkmcnt(2)
	v_cvt_pk_bf16_f32 v2, v10, v11
	v_cvt_pk_bf16_f32 v3, v12, v13
	s_waitcnt lgkmcnt(1)
	v_cvt_pk_bf16_f32 v4, v14, v15
	v_cvt_pk_bf16_f32 v5, v16, v17
	ds_read_b128 v[10:13], v20 offset:80
	global_store_dwordx4 v[18:19], v[2:5], off offset:16
	s_add_i32 s34, s34, s94
	s_add_i32 s19, s19, s20
	s_waitcnt lgkmcnt(1)
	v_cvt_pk_bf16_f32 v2, v6, v7
	v_cvt_pk_bf16_f32 v3, v8, v9
	s_waitcnt lgkmcnt(0)
	v_cvt_pk_bf16_f32 v4, v10, v11
	v_cvt_pk_bf16_f32 v5, v12, v13
	ds_read_b128 v[6:9], v20 offset:96
	ds_read_b128 v[10:13], v20 offset:112
	global_store_dwordx4 v[18:19], v[2:5], off offset:32
	s_cmpk_lt_i32 s35, 0x100
	ds_read_b128 v[14:17], v20 offset:240
	s_waitcnt lgkmcnt(2)
	v_cvt_pk_bf16_f32 v2, v6, v7
	v_cvt_pk_bf16_f32 v3, v8, v9
	s_waitcnt lgkmcnt(1)
	v_cvt_pk_bf16_f32 v4, v10, v11
	v_cvt_pk_bf16_f32 v5, v12, v13
	ds_read_b128 v[6:9], v20 offset:128
	ds_read_b128 v[10:13], v20 offset:144
	global_store_dwordx4 v[18:19], v[2:5], off offset:48
	s_waitcnt lgkmcnt(1)
	s_nop 0
	v_cvt_pk_bf16_f32 v2, v6, v7
	v_cvt_pk_bf16_f32 v3, v8, v9
	s_waitcnt lgkmcnt(0)
	v_cvt_pk_bf16_f32 v4, v10, v11
	v_cvt_pk_bf16_f32 v5, v12, v13
	ds_read_b128 v[6:9], v20 offset:160
	ds_read_b128 v[10:13], v20 offset:176
	global_store_dwordx4 v[18:19], v[2:5], off offset:64
	s_waitcnt lgkmcnt(1)
	s_nop 0
	v_cvt_pk_bf16_f32 v2, v6, v7
	v_cvt_pk_bf16_f32 v3, v8, v9
	s_waitcnt lgkmcnt(0)
	v_cvt_pk_bf16_f32 v4, v10, v11
	v_cvt_pk_bf16_f32 v5, v12, v13
	ds_read_b128 v[6:9], v20 offset:192
	ds_read_b128 v[10:13], v20 offset:208
	global_store_dwordx4 v[18:19], v[2:5], off offset:80
	s_waitcnt lgkmcnt(1)
	s_nop 0
	v_cvt_pk_bf16_f32 v2, v6, v7
	v_cvt_pk_bf16_f32 v3, v8, v9
	s_waitcnt lgkmcnt(0)
	v_cvt_pk_bf16_f32 v4, v10, v11
	v_cvt_pk_bf16_f32 v5, v12, v13
	ds_read_b128 v[6:9], v20 offset:224
	global_store_dwordx4 v[18:19], v[2:5], off offset:96
	s_waitcnt lgkmcnt(0)
	s_nop 0
	v_cvt_pk_bf16_f32 v2, v6, v7
	v_cvt_pk_bf16_f32 v3, v8, v9
	v_cvt_pk_bf16_f32 v4, v14, v15
	v_cvt_pk_bf16_f32 v5, v16, v17
	global_store_dwordx4 v[18:19], v[2:5], off offset:112
	s_barrier
	s_cbranch_scc1 .LBB0_1120

;     ...
;   for (int kt = 0; kt < nk; ++kt) {
;     const int kn = (kt + 1 < nk) ? kt + 1 : kt;
;     GM_LOAD2(kn * 64, kn * bkstep)
;     __builtin_amdgcn_sched_barrier(0);
;     const char* As = smem + (kt & 1) * 2 * TILE_B;
;     const char* Bs = As + TILE_B;
;     if constexpr (HOIST) {
;       bf16x8 fa0[4], fa1[4], fb0[4], fb1[4];
; #pragma unroll
;       for (int st = 0; st < 4; ++st) {
;         fa0[st] = *(const bf16x8*)(As + aoff + st * 32);
;         fb0[st] = *(const bf16x8*)(Bs + boff + st * 32);
;         fa1[st] = *(const bf16x8*)(As + aoff + 32 * LSTR + st * 32);
;         fb1[st] = *(const bf16x8*)(Bs + boff + 32 * LSTR + st * 32);
;       }
;       __builtin_amdgcn_sched_barrier(0);
; #pragma unroll
;       for (int st = 0; st < 4; ++st) {
;         acc[0][0] = mfma32(fa0[st], fb0[st], acc[0][0]);
;         acc[0][1] = mfma32(fa0[st], fb1[st], acc[0][1]);
;         acc[1][0] = mfma32(fa1[st], fb0[st], acc[1][0]);
;         acc[1][1] = mfma32(fa1[st], fb1[st], acc[1][1]);
;       }
;     } else {
; #pragma unroll
;       for (int st = 0; st < 4; ++st) {
;         bf16x8 a0 = *(const bf16x8*)(As + aoff + st * 32);
;         bf16x8 a1 = *(const bf16x8*)(As + aoff + 32 * LSTR + st * 32);
;         bf16x8 b0 = *(const bf16x8*)(Bs + boff + st * 32);
;         bf16x8 b1 = *(const bf16x8*)(Bs + boff + 32 * LSTR + st * 32);
;         acc[0][0] = mfma32(a0, b0, acc[0][0]);
;         acc[0][1] = mfma32(a0, b1, acc[0][1]);
;         acc[1][0] = mfma32(a1, b0, acc[1][0]);
;         acc[1][1] = mfma32(a1, b1, acc[1][1]);
;       }
;     }
;     __builtin_amdgcn_sched_barrier(0);
;     {
;       char* Ad = smem + ((kt + 1) & 1) * 2 * TILE_B;
;       GM_STORE(Ad)
;     }
;     __syncthreads();
;   }
.LBB0_1401:
	s_and_b32 s26, s6, 2
	s_mulk_i32 s26, 0x4800
	v_add3_u32 v130, s26, v163, v164
	s_setprio 1
	v_add3_u32 v169, s26, v165, v164
	ds_read_b128 v[202:205], v130 offset:0
	ds_read_b128 v[206:209], v169 offset:18432
	ds_read_b128 v[214:217], v130 offset:4608
	ds_read_b128 v[210:213], v169 offset:23040
	s_waitcnt lgkmcnt(2)
	v_mfma_f32_32x32x16_bf16 v[50:65], v[202:205], v[206:209], v[50:65]
	ds_read_b128 v[218:221], v130 offset:32
	s_waitcnt lgkmcnt(2)
	v_mfma_f32_32x32x16_bf16 v[2:17], v[214:217], v[206:209], v[2:17]
	ds_read_b128 v[206:209], v169 offset:18464
	s_waitcnt lgkmcnt(2)
	v_mfma_f32_32x32x16_bf16 v[18:33], v[202:205], v[210:213], v[18:33]
	ds_read_b128 v[202:205], v130 offset:4640
	v_mfma_f32_32x32x16_bf16 v[34:49], v[214:217], v[210:213], v[34:49]
	ds_read_b128 v[210:213], v169 offset:23072
	s_waitcnt lgkmcnt(2)
	v_mfma_f32_32x32x16_bf16 v[50:65], v[218:221], v[206:209], v[50:65]
	ds_read_b128 v[214:217], v130 offset:64
	s_waitcnt lgkmcnt(2)
	v_mfma_f32_32x32x16_bf16 v[2:17], v[202:205], v[206:209], v[2:17]
	ds_read_b128 v[206:209], v169 offset:18496
	s_waitcnt lgkmcnt(2)
	v_mfma_f32_32x32x16_bf16 v[18:33], v[218:221], v[210:213], v[18:33]
	ds_read_b128 v[218:221], v130 offset:4672
	v_mfma_f32_32x32x16_bf16 v[34:49], v[202:205], v[210:213], v[34:49]
	ds_read_b128 v[210:213], v169 offset:23104
	s_waitcnt lgkmcnt(2)
	v_mfma_f32_32x32x16_bf16 v[50:65], v[214:217], v[206:209], v[50:65]
	ds_read_b128 v[202:205], v130 offset:96
	s_waitcnt lgkmcnt(2)
	v_mfma_f32_32x32x16_bf16 v[2:17], v[218:221], v[206:209], v[2:17]
	ds_read_b128 v[206:209], v169 offset:18528
	s_waitcnt lgkmcnt(2)
	v_mfma_f32_32x32x16_bf16 v[18:33], v[214:217], v[210:213], v[18:33]
	ds_read_b128 v[214:217], v130 offset:4704
	v_mfma_f32_32x32x16_bf16 v[34:49], v[218:221], v[210:213], v[34:49]
	ds_read_b128 v[210:213], v169 offset:23136
	s_waitcnt lgkmcnt(2)
	v_mfma_f32_32x32x16_bf16 v[50:65], v[202:205], v[206:209], v[50:65]
	s_waitcnt lgkmcnt(1)
	v_mfma_f32_32x32x16_bf16 v[2:17], v[214:217], v[206:209], v[2:17]
	s_waitcnt lgkmcnt(0)
	v_mfma_f32_32x32x16_bf16 v[18:33], v[202:205], v[210:213], v[18:33]
	v_mfma_f32_32x32x16_bf16 v[34:49], v[214:217], v[210:213], v[34:49]
	s_add_i32 s6, s6, 2
	s_and_b32 s26, s6, 2
	s_add_u32 s10, s10, 0x80
	s_mulk_i32 s26, 0x4800
	s_addc_u32 s11, s11, 0
	v_add_u32_e32 v130, s26, v137
	s_cmpk_lg_i32 s10, 0x1f00
	s_waitcnt vmcnt(7)
	ds_write_b128 v130, v[170:173]
	v_lshl_add_u64 v[170:171], v[158:159], 0, s[10:11]
	v_add_co_u32_e32 v170, vcc, s18, v170
	s_nop 1
	v_addc_co_u32_e32 v171, vcc, 0, v171, vcc
	global_load_dwordx4 v[170:173], v[170:171], off offset:128
	s_waitcnt vmcnt(7)
	ds_write_b128 v130, v[174:177] offset:4608
	v_lshl_add_u64 v[174:175], v[158:159], 0, s[10:11]
	v_add_co_u32_e32 v174, vcc, s19, v174
	s_nop 1
	v_addc_co_u32_e32 v175, vcc, 0, v175, vcc
	global_load_dwordx4 v[174:177], v[174:175], off offset:128
	s_waitcnt vmcnt(7)
	ds_write_b128 v130, v[178:181] offset:9216
	v_lshl_add_u64 v[178:179], v[158:159], 0, s[10:11]
	v_add_co_u32_e32 v178, vcc, s20, v178
	s_nop 1
	v_addc_co_u32_e32 v179, vcc, 0, v179, vcc
	global_load_dwordx4 v[178:181], v[178:179], off offset:128
	s_waitcnt vmcnt(7)
	ds_write_b128 v130, v[182:185] offset:13824
	v_lshl_add_u64 v[182:183], v[158:159], 0, s[10:11]
	v_add_co_u32_e32 v182, vcc, s21, v182
	s_nop 1
	v_addc_co_u32_e32 v183, vcc, 0, v183, vcc
	global_load_dwordx4 v[182:185], v[182:183], off offset:128
	s_waitcnt vmcnt(7)
	ds_write_b128 v130, v[186:189] offset:18432
	v_lshl_add_u64 v[186:187], v[160:161], 0, s[10:11]
	v_add_co_u32_e32 v186, vcc, s22, v186
	s_nop 1
	v_addc_co_u32_e32 v187, vcc, 0, v187, vcc
	global_load_dwordx4 v[186:189], v[186:187], off offset:384
	s_waitcnt vmcnt(7)
	ds_write_b128 v130, v[190:193] offset:23040
	v_lshl_add_u64 v[190:191], v[160:161], 0, s[10:11]
	v_add_co_u32_e32 v190, vcc, s23, v190
	s_nop 1
	v_addc_co_u32_e32 v191, vcc, 0, v191, vcc
	global_load_dwordx4 v[190:193], v[190:191], off offset:384
	s_waitcnt vmcnt(7)
	ds_write_b128 v130, v[194:197] offset:27648
	v_lshl_add_u64 v[194:195], v[160:161], 0, s[10:11]
	v_add_co_u32_e32 v194, vcc, s24, v194
	s_nop 1
	v_addc_co_u32_e32 v195, vcc, 0, v195, vcc
	global_load_dwordx4 v[194:197], v[194:195], off offset:384
	s_waitcnt vmcnt(7)
	ds_write_b128 v130, v[198:201] offset:32256
	v_lshl_add_u64 v[198:199], v[160:161], 0, s[10:11]
	v_add_co_u32_e32 v198, vcc, s25, v198
	s_nop 1
	v_addc_co_u32_e32 v199, vcc, 0, v199, vcc
	global_load_dwordx4 v[198:201], v[198:199], off offset:384
	s_setprio 0
	s_waitcnt lgkmcnt(0)
	s_barrier
	s_cbranch_scc1 .LBB0_1401
;     ...
;   for (int kt = 0; kt < nk; ++kt) {
;     const int kn = (kt + 1 < nk) ? kt + 1 : kt;
;     GM_LOAD2(kn * 64, kn * bkstep)
;     __builtin_amdgcn_sched_barrier(0);
;     const char* As = smem + (kt & 1) * 2 * TILE_B;
;     const char* Bs = As + TILE_B;
;     if constexpr (HOIST) {
;       bf16x8 fa0[4], fa1[4], fb0[4], fb1[4];
; #pragma unroll
;       for (int st = 0; st < 4; ++st) {
;         fa0[st] = *(const bf16x8*)(As + aoff + st * 32);
;         fb0[st] = *(const bf16x8*)(Bs + boff + st * 32);
;         fa1[st] = *(const bf16x8*)(As + aoff + 32 * LSTR + st * 32);
;         fb1[st] = *(const bf16x8*)(Bs + boff + 32 * LSTR + st * 32);
;       }
;       __builtin_amdgcn_sched_barrier(0);
; #pragma unroll
;       for (int st = 0; st < 4; ++st) {
;         acc[0][0] = mfma32(fa0[st], fb0[st], acc[0][0]);
;         acc[0][1] = mfma32(fa0[st], fb1[st], acc[0][1]);
;         acc[1][0] = mfma32(fa1[st], fb0[st], acc[1][0]);
;         acc[1][1] = mfma32(fa1[st], fb1[st], acc[1][1]);
;       }
;     } else {
; #pragma unroll
;       for (int st = 0; st < 4; ++st) {
;         bf16x8 a0 = *(const bf16x8*)(As + aoff + st * 32);
;         bf16x8 a1 = *(const bf16x8*)(As + aoff + 32 * LSTR + st * 32);
;         bf16x8 b0 = *(const bf16x8*)(Bs + boff + st * 32);
;         bf16x8 b1 = *(const bf16x8*)(Bs + boff + 32 * LSTR + st * 32);
;         acc[0][0] = mfma32(a0, b0, acc[0][0]);
;         acc[0][1] = mfma32(a0, b1, acc[0][1]);
;         acc[1][0] = mfma32(a1, b0, acc[1][0]);
;         acc[1][1] = mfma32(a1, b1, acc[1][1]);
;       }
;     }
;     __builtin_amdgcn_sched_barrier(0);
;     {
;       char* Ad = smem + ((kt + 1) & 1) * 2 * TILE_B;
;       GM_STORE(Ad)
;     }
;     __syncthreads();
;   }
	s_and_b32 s26, s6, 2
	s_mulk_i32 s26, 0x4800
	v_add3_u32 v130, s26, v163, v164
	s_setprio 1
	v_add3_u32 v169, s26, v165, v164
	ds_read_b128 v[202:205], v130 offset:0
	ds_read_b128 v[206:209], v169 offset:18432
	ds_read_b128 v[214:217], v130 offset:4608
	ds_read_b128 v[210:213], v169 offset:23040
	s_waitcnt lgkmcnt(2)
	v_mfma_f32_32x32x16_bf16 v[50:65], v[202:205], v[206:209], v[50:65]
	ds_read_b128 v[218:221], v130 offset:32
	s_waitcnt lgkmcnt(2)
	v_mfma_f32_32x32x16_bf16 v[2:17], v[214:217], v[206:209], v[2:17]
	ds_read_b128 v[206:209], v169 offset:18464
	s_waitcnt lgkmcnt(2)
	v_mfma_f32_32x32x16_bf16 v[18:33], v[202:205], v[210:213], v[18:33]
	ds_read_b128 v[202:205], v130 offset:4640
	v_mfma_f32_32x32x16_bf16 v[34:49], v[214:217], v[210:213], v[34:49]
	ds_read_b128 v[210:213], v169 offset:23072
	s_waitcnt lgkmcnt(2)
	v_mfma_f32_32x32x16_bf16 v[50:65], v[218:221], v[206:209], v[50:65]
	ds_read_b128 v[214:217], v130 offset:64
	s_waitcnt lgkmcnt(2)
	v_mfma_f32_32x32x16_bf16 v[2:17], v[202:205], v[206:209], v[2:17]
	ds_read_b128 v[206:209], v169 offset:18496
	s_waitcnt lgkmcnt(2)
	v_mfma_f32_32x32x16_bf16 v[18:33], v[218:221], v[210:213], v[18:33]
	ds_read_b128 v[218:221], v130 offset:4672
	v_mfma_f32_32x32x16_bf16 v[34:49], v[202:205], v[210:213], v[34:49]
	ds_read_b128 v[210:213], v169 offset:23104
	s_waitcnt lgkmcnt(2)
	v_mfma_f32_32x32x16_bf16 v[50:65], v[214:217], v[206:209], v[50:65]
	ds_read_b128 v[202:205], v130 offset:96
	s_waitcnt lgkmcnt(2)
	v_mfma_f32_32x32x16_bf16 v[2:17], v[218:221], v[206:209], v[2:17]
	ds_read_b128 v[206:209], v169 offset:18528
	s_waitcnt lgkmcnt(2)
	v_mfma_f32_32x32x16_bf16 v[18:33], v[214:217], v[210:213], v[18:33]
	ds_read_b128 v[214:217], v130 offset:4704
	v_mfma_f32_32x32x16_bf16 v[34:49], v[218:221], v[210:213], v[34:49]
	ds_read_b128 v[210:213], v169 offset:23136
	s_waitcnt lgkmcnt(2)
	v_mfma_f32_32x32x16_bf16 v[50:65], v[202:205], v[206:209], v[50:65]
	s_waitcnt lgkmcnt(1)
	v_mfma_f32_32x32x16_bf16 v[2:17], v[214:217], v[206:209], v[2:17]
	s_waitcnt lgkmcnt(0)
	v_mfma_f32_32x32x16_bf16 v[18:33], v[202:205], v[210:213], v[18:33]
	v_mfma_f32_32x32x16_bf16 v[34:49], v[214:217], v[210:213], v[34:49]
	s_add_i32 s6, s6, 2
	s_and_b32 s26, s6, 2
	s_add_u32 s10, s10, 0x80
	s_mulk_i32 s26, 0x4800
	s_addc_u32 s11, s11, 0
	v_add_u32_e32 v130, s26, v137
	s_waitcnt vmcnt(7)
	ds_write_b128 v130, v[170:173]
	s_waitcnt vmcnt(6)
	ds_write_b128 v130, v[174:177] offset:4608
	s_waitcnt vmcnt(5)
	ds_write_b128 v130, v[178:181] offset:9216
	s_waitcnt vmcnt(4)
	ds_write_b128 v130, v[182:185] offset:13824
	s_waitcnt vmcnt(3)
	ds_write_b128 v130, v[186:189] offset:18432
	s_waitcnt vmcnt(2)
	ds_write_b128 v130, v[190:193] offset:23040
	s_waitcnt vmcnt(1)
	ds_write_b128 v130, v[194:197] offset:27648
	s_waitcnt vmcnt(0)
	ds_write_b128 v130, v[198:201] offset:32256
	s_setprio 0
	s_waitcnt lgkmcnt(0)
	s_barrier
	v_lshl_add_u64 v[174:175], v[158:159], 0, s[10:11]
	v_add_co_u32_e32 v158, vcc, 0xdf00000, v174
	v_lshl_add_u64 v[190:191], v[160:161], 0, s[10:11]
	s_nop 0
	v_addc_co_u32_e32 v159, vcc, 0, v175, vcc
	v_add_co_u32_e32 v170, vcc, 0xdf80000, v174
	s_nop 1
	v_addc_co_u32_e32 v171, vcc, 0, v175, vcc
	v_add_co_u32_e32 v176, vcc, 0xe000000, v174
	s_nop 0
	v_addc_co_u32_e32 v177, vcc, 0, v175, vcc
	v_add_co_u32_e32 v178, vcc, 0xe080000, v174
	s_nop 1
	v_addc_co_u32_e32 v179, vcc, 0, v175, vcc
	v_add_co_u32_e32 v182, vcc, 0x35d31000, v190
	s_nop 0
	v_addc_co_u32_e32 v183, vcc, 0, v191, vcc
	v_add_co_u32_e32 v186, vcc, 0x35db1000, v190
	s_nop 1
	v_addc_co_u32_e32 v187, vcc, 0, v191, vcc
	v_add_co_u32_e32 v192, vcc, 0x35e31000, v190
	s_nop 0
	v_addc_co_u32_e32 v193, vcc, 0, v191, vcc
	v_add_co_u32_e32 v194, vcc, 0x35eb1000, v190
	s_nop 1
	v_addc_co_u32_e32 v195, vcc, 0, v191, vcc
	s_nop 0
	v_add3_u32 v130, s26, v163, v164
	s_setprio 1
	v_add3_u32 v169, s26, v165, v164
	ds_read_b128 v[198:201], v130 offset:0
	ds_read_b128 v[202:205], v169 offset:18432
	ds_read_b128 v[210:213], v130 offset:4608
	ds_read_b128 v[206:209], v169 offset:23040
	s_waitcnt lgkmcnt(2)
	v_mfma_f32_32x32x16_bf16 v[50:65], v[198:201], v[202:205], v[50:65]
	ds_read_b128 v[214:217], v130 offset:32
	s_waitcnt lgkmcnt(2)
	v_mfma_f32_32x32x16_bf16 v[2:17], v[210:213], v[202:205], v[2:17]
	ds_read_b128 v[202:205], v169 offset:18464
	s_waitcnt lgkmcnt(2)
	v_mfma_f32_32x32x16_bf16 v[18:33], v[198:201], v[206:209], v[18:33]
	ds_read_b128 v[198:201], v130 offset:4640
	v_mfma_f32_32x32x16_bf16 v[34:49], v[210:213], v[206:209], v[34:49]
	ds_read_b128 v[206:209], v169 offset:23072
	s_waitcnt lgkmcnt(2)
	v_mfma_f32_32x32x16_bf16 v[50:65], v[214:217], v[202:205], v[50:65]
	ds_read_b128 v[210:213], v130 offset:64
	s_waitcnt lgkmcnt(2)
	v_mfma_f32_32x32x16_bf16 v[2:17], v[198:201], v[202:205], v[2:17]
	ds_read_b128 v[202:205], v169 offset:18496
	s_waitcnt lgkmcnt(2)
	v_mfma_f32_32x32x16_bf16 v[18:33], v[214:217], v[206:209], v[18:33]
	ds_read_b128 v[214:217], v130 offset:4672
	v_mfma_f32_32x32x16_bf16 v[34:49], v[198:201], v[206:209], v[34:49]
	ds_read_b128 v[206:209], v169 offset:23104
	s_waitcnt lgkmcnt(2)
	v_mfma_f32_32x32x16_bf16 v[50:65], v[210:213], v[202:205], v[50:65]
	ds_read_b128 v[198:201], v130 offset:96
	s_waitcnt lgkmcnt(2)
	v_mfma_f32_32x32x16_bf16 v[2:17], v[214:217], v[202:205], v[2:17]
	ds_read_b128 v[202:205], v169 offset:18528
	s_waitcnt lgkmcnt(2)
	v_mfma_f32_32x32x16_bf16 v[18:33], v[210:213], v[206:209], v[18:33]
	ds_read_b128 v[210:213], v130 offset:4704
	v_mfma_f32_32x32x16_bf16 v[34:49], v[214:217], v[206:209], v[34:49]
	ds_read_b128 v[206:209], v169 offset:23136
	s_waitcnt lgkmcnt(2)
	v_mfma_f32_32x32x16_bf16 v[50:65], v[198:201], v[202:205], v[50:65]
	s_waitcnt lgkmcnt(1)
	v_mfma_f32_32x32x16_bf16 v[2:17], v[210:213], v[202:205], v[2:17]
	s_waitcnt lgkmcnt(0)
	v_mfma_f32_32x32x16_bf16 v[18:33], v[198:201], v[206:209], v[18:33]
	v_mfma_f32_32x32x16_bf16 v[34:49], v[210:213], v[206:209], v[34:49]
	s_setprio 0
	s_waitcnt lgkmcnt(0)
	s_barrier
; __device__ __forceinline__ void acc_to_lds(const f32x16 (&acc)[2][2], float* cs) {
;   const int tid = threadIdx.x, lane = tid & 63, wave = tid >> 6;
;   const int wm = wave >> 1, wn = wave & 1;
; #pragma unroll
;   for (int i = 0; i < 2; ++i)
; #pragma unroll
;     for (int j = 0; j < 2; ++j)
; #pragma unroll
;       for (int r = 0; r < 16; ++r) {
;         int row = wm * 64 + i * 32 + (r & 3) + 8 * (r >> 2) + 4 * (lane >> 5);
;         int col = wn * 64 + j * 32 + (lane & 31);
;         cs[row * CSTR + col] = acc[i][j][r];
;       }
;   __syncthreads();
; __device__ __forceinline__ void fourier_half_tile(const Params& P, bool isctx, int b, int mt, int nt, char* smem) {
;     ...
;       u16* d1 = WSP(u16, OFF_FTO) + (rowbase + k) * 256 + nt * 128 + half * 64;
;       u16* d2 = WSP(u16, OFF_FTO) + (rowbase + (k > 0 ? N - k : 0)) * 256 + nt * 128 + half * 64;
; #pragma unroll
;       for (int q = 0; q < 8; ++q) {
;         float4 a = *(const float4*)(cs + r * CSTR + half * 64 + q * 8);
;         float4 c = *(const float4*)(cs + r * CSTR + half * 64 + q * 8 + 4);
;         uint4 o1, o2;
;         o1.x = pack2(pacc[q * 8 + 0] + a.x, pacc[q * 8 + 1] + a.y); o1.y = pack2(pacc[q * 8 + 2] + a.z, pacc[q * 8 + 3] + a.w);
;         o1.z = pack2(pacc[q * 8 + 4] + c.x, pacc[q * 8 + 5] + c.y); o1.w = pack2(pacc[q * 8 + 6] + c.z, pacc[q * 8 + 7] + c.w);
;         o2.x = pack2(pacc[q * 8 + 0] - a.x, pacc[q * 8 + 1] - a.y); o2.y = pack2(pacc[q * 8 + 2] - a.z, pacc[q * 8 + 3] - a.w);
;         o2.z = pack2(pacc[q * 8 + 4] - c.x, pacc[q * 8 + 5] - c.y); o2.w = pack2(pacc[q * 8 + 6] - c.z, pacc[q * 8 + 7] - c.w);
;         *(uint4*)(d1 + q * 8) = o1;
;         if (k > 0) *(uint4*)(d2 + q * 8) = o2;
	ds_write2_b32 v166, v50, v18 offset1:32
	ds_write2_b32 v166, v51, v19 offset0:132 offset1:164
	v_add_u32_e32 v18, 0x400, v166
	ds_write2_b32 v18, v52, v20 offset0:8 offset1:40
	ds_write2_b32 v18, v53, v21 offset0:140 offset1:172
	v_add_u32_e32 v18, 0x1000, v166
	ds_write2_b32 v18, v54, v22 offset0:32 offset1:64
	ds_write2_b32 v18, v55, v23 offset0:164 offset1:196
	v_add_u32_e32 v18, 0x1400, v166
	ds_write2_b32 v18, v56, v24 offset0:40 offset1:72
	ds_write2_b32 v18, v57, v25 offset0:172 offset1:204
	v_add_u32_e32 v18, 0x2000, v166
	ds_write2_b32 v18, v58, v26 offset0:64 offset1:96
	ds_write2_b32 v18, v59, v27 offset0:196 offset1:228
	v_add_u32_e32 v18, 0x2400, v166
	ds_write2_b32 v18, v60, v28 offset0:72 offset1:104
	ds_write2_b32 v18, v61, v29 offset0:204 offset1:236
	v_add_u32_e32 v18, 0x3000, v166
	ds_write2_b32 v18, v62, v30 offset0:96 offset1:128
	v_add_u32_e32 v18, 0x3200, v166
	ds_write2_b32 v18, v63, v31 offset0:100 offset1:132
	v_add_u32_e32 v18, 0x3400, v166
	ds_write2_b32 v18, v64, v32 offset0:104 offset1:136
	v_add_u32_e32 v18, 0x3600, v166
	ds_write2_b32 v18, v65, v33 offset0:108 offset1:140
	v_add_u32_e32 v18, 0x4000, v166
	ds_write2_b32 v18, v2, v34 offset0:128 offset1:160
	v_add_u32_e32 v2, 0x4400, v166
	ds_write2_b32 v2, v3, v35 offset0:4 offset1:36
	ds_write2_b32 v2, v4, v36 offset0:136 offset1:168
	v_add_u32_e32 v2, 0x4800, v166
	ds_write2_b32 v2, v5, v37 offset0:12 offset1:44
	v_add_u32_e32 v2, 0x5000, v166
	ds_write2_b32 v2, v6, v38 offset0:160 offset1:192
	v_add_u32_e32 v2, 0x5400, v166
	ds_write2_b32 v2, v7, v39 offset0:36 offset1:68
	ds_write2_b32 v2, v8, v40 offset0:168 offset1:200
	v_add_u32_e32 v2, 0x5800, v166
	ds_write2_b32 v2, v9, v41 offset0:44 offset1:76
	v_add_u32_e32 v2, 0x6000, v166
	ds_write2_b32 v2, v10, v42 offset0:192 offset1:224
	v_add_u32_e32 v2, 0x6400, v166
	ds_write2_b32 v2, v11, v43 offset0:68 offset1:100
	ds_write2_b32 v2, v12, v44 offset0:200 offset1:232
	v_add_u32_e32 v2, 0x6800, v166
	ds_write2_b32 v2, v13, v45 offset0:76 offset1:108
	v_add_u32_e32 v2, 0x7200, v166
	ds_write2_b32 v2, v14, v46 offset0:96 offset1:128
	v_add_u32_e32 v2, 0x7400, v166
	ds_write2_b32 v2, v15, v47 offset0:100 offset1:132
	v_add_u32_e32 v2, 0x7600, v166
	ds_write2_b32 v2, v16, v48 offset0:104 offset1:136
	v_add_u32_e32 v2, 0x7800, v166
	s_mov_b64 s[10:11], -1
	s_and_b64 vcc, exec, s[8:9]
	ds_write2_b32 v2, v17, v49 offset0:108 offset1:140
	s_waitcnt lgkmcnt(0)
	s_barrier
	s_cbranch_vccz .LBB0_1420
	ds_read_b128 v[2:5], v167
	ds_read_b128 v[6:9], v167 offset:16
	s_waitcnt lgkmcnt(1)
	v_add_f32_e32 v10, v78, v2
	v_add_f32_e32 v11, v79, v3
	v_sub_f32_e32 v2, v78, v2
	v_sub_f32_e32 v3, v79, v3
	v_add_f32_e32 v12, v80, v4
	v_add_f32_e32 v13, v81, v5
	v_cvt_pk_bf16_f32 v2, v2, v3
	v_sub_f32_e32 v3, v80, v4
	v_sub_f32_e32 v4, v81, v5
	v_cvt_pk_bf16_f32 v10, v10, v11
	v_cvt_pk_bf16_f32 v11, v12, v13
	s_waitcnt lgkmcnt(0)
	v_add_f32_e32 v12, v74, v6
	v_add_f32_e32 v13, v75, v7
	v_cvt_pk_bf16_f32 v3, v3, v4
	v_sub_f32_e32 v4, v74, v6
	v_sub_f32_e32 v5, v75, v7
	v_cvt_pk_bf16_f32 v12, v12, v13
	v_add_f32_e32 v13, v76, v8
	v_cvt_pk_bf16_f32 v4, v4, v5
	v_sub_f32_e32 v5, v76, v8
	v_add_f32_e32 v14, v77, v9
	v_cvt_pk_bf16_f32 v13, v13, v14
	v_sub_f32_e32 v6, v77, v9
	v_cvt_pk_bf16_f32 v5, v5, v6
	global_store_dwordx4 v[148:149], v[10:13], off
	s_and_saveexec_b64 s[10:11], s[2:3]
	s_cbranch_execz .LBB0_1405
	global_store_dwordx4 v[150:151], v[2:5], off

;     ...
;   for (int kt = 0; kt < nk; ++kt) {
;     const int kn = (kt + 1 < nk) ? kt + 1 : kt;
;     GM_LOAD2(kn * 64, kn * bkstep)
;     __builtin_amdgcn_sched_barrier(0);
;     const char* As = smem + (kt & 1) * 2 * TILE_B;
;     const char* Bs = As + TILE_B;
;     if constexpr (HOIST) {
;       bf16x8 fa0[4], fa1[4], fb0[4], fb1[4];
; #pragma unroll
;       for (int st = 0; st < 4; ++st) {
;         fa0[st] = *(const bf16x8*)(As + aoff + st * 32);
;         fb0[st] = *(const bf16x8*)(Bs + boff + st * 32);
;         fa1[st] = *(const bf16x8*)(As + aoff + 32 * LSTR + st * 32);
;         fb1[st] = *(const bf16x8*)(Bs + boff + 32 * LSTR + st * 32);
;       }
;       __builtin_amdgcn_sched_barrier(0);
; #pragma unroll
;       for (int st = 0; st < 4; ++st) {
;         acc[0][0] = mfma32(fa0[st], fb0[st], acc[0][0]);
;         acc[0][1] = mfma32(fa0[st], fb1[st], acc[0][1]);
;         acc[1][0] = mfma32(fa1[st], fb0[st], acc[1][0]);
;         acc[1][1] = mfma32(fa1[st], fb1[st], acc[1][1]);
;       }
;     } else {
; #pragma unroll
;       for (int st = 0; st < 4; ++st) {
;         bf16x8 a0 = *(const bf16x8*)(As + aoff + st * 32);
;         bf16x8 a1 = *(const bf16x8*)(As + aoff + 32 * LSTR + st * 32);
;         bf16x8 b0 = *(const bf16x8*)(Bs + boff + st * 32);
;         bf16x8 b1 = *(const bf16x8*)(Bs + boff + 32 * LSTR + st * 32);
;         acc[0][0] = mfma32(a0, b0, acc[0][0]);
;         acc[0][1] = mfma32(a0, b1, acc[0][1]);
;         acc[1][0] = mfma32(a1, b0, acc[1][0]);
;         acc[1][1] = mfma32(a1, b1, acc[1][1]);
;       }
;     }
;     __builtin_amdgcn_sched_barrier(0);
;     {
;       char* Ad = smem + ((kt + 1) & 1) * 2 * TILE_B;
;       GM_STORE(Ad)
;     }
;     __syncthreads();
;   }
.LBB0_1640:
	s_and_b32 s40, s39, 2
	s_mulk_i32 s40, 0x4800
	v_add3_u32 v220, s40, v137, v164
	s_setprio 1
	v_add3_u32 v221, s40, v165, v164
	ds_read_b128 v[200:203], v220 offset:0
	ds_read_b128 v[204:207], v221 offset:18432
	ds_read_b128 v[212:215], v220 offset:4608
	ds_read_b128 v[208:211], v221 offset:23040
	s_waitcnt lgkmcnt(2)
	v_mfma_f32_32x32x16_bf16 v[34:49], v[200:203], v[204:207], v[34:49]
	ds_read_b128 v[216:219], v220 offset:32
	s_waitcnt lgkmcnt(2)
	v_mfma_f32_32x32x16_bf16 v[18:33], v[212:215], v[204:207], v[18:33]
	ds_read_b128 v[204:207], v221 offset:18464
	s_waitcnt lgkmcnt(2)
	v_mfma_f32_32x32x16_bf16 v[2:17], v[200:203], v[208:211], v[2:17]
	ds_read_b128 v[200:203], v220 offset:4640
	v_mfma_f32_32x32x16_bf16 v[50:65], v[212:215], v[208:211], v[50:65]
	ds_read_b128 v[208:211], v221 offset:23072
	s_waitcnt lgkmcnt(2)
	v_mfma_f32_32x32x16_bf16 v[34:49], v[216:219], v[204:207], v[34:49]
	ds_read_b128 v[212:215], v220 offset:64
	s_waitcnt lgkmcnt(2)
	v_mfma_f32_32x32x16_bf16 v[18:33], v[200:203], v[204:207], v[18:33]
	ds_read_b128 v[204:207], v221 offset:18496
	s_waitcnt lgkmcnt(2)
	v_mfma_f32_32x32x16_bf16 v[2:17], v[216:219], v[208:211], v[2:17]
	ds_read_b128 v[216:219], v220 offset:4672
	v_mfma_f32_32x32x16_bf16 v[50:65], v[200:203], v[208:211], v[50:65]
	ds_read_b128 v[208:211], v221 offset:23104
	s_waitcnt lgkmcnt(2)
	v_mfma_f32_32x32x16_bf16 v[34:49], v[212:215], v[204:207], v[34:49]
	ds_read_b128 v[200:203], v220 offset:96
	s_waitcnt lgkmcnt(2)
	v_mfma_f32_32x32x16_bf16 v[18:33], v[216:219], v[204:207], v[18:33]
	ds_read_b128 v[204:207], v221 offset:18528
	s_waitcnt lgkmcnt(2)
	v_mfma_f32_32x32x16_bf16 v[2:17], v[212:215], v[208:211], v[2:17]
	ds_read_b128 v[212:215], v220 offset:4704
	v_mfma_f32_32x32x16_bf16 v[50:65], v[216:219], v[208:211], v[50:65]
	ds_read_b128 v[208:211], v221 offset:23136
	s_waitcnt lgkmcnt(2)
	v_mfma_f32_32x32x16_bf16 v[34:49], v[200:203], v[204:207], v[34:49]
	s_waitcnt lgkmcnt(1)
	v_mfma_f32_32x32x16_bf16 v[18:33], v[212:215], v[204:207], v[18:33]
	s_waitcnt lgkmcnt(0)
	v_mfma_f32_32x32x16_bf16 v[2:17], v[200:203], v[208:211], v[2:17]
	v_mfma_f32_32x32x16_bf16 v[50:65], v[212:215], v[208:211], v[50:65]
	s_add_i32 s39, s39, 2
	s_and_b32 s40, s39, 2
	s_mulk_i32 s40, 0x4800
	s_add_i32 s6, s6, -1
	v_add_u32_e32 v200, s40, v135
	v_lshl_add_u64 v[148:149], v[148:149], 0, s[8:9]
	v_lshl_add_u64 v[150:151], v[150:151], 0, s[8:9]
	v_lshl_add_u64 v[152:153], v[152:153], 0, s[8:9]
	v_lshl_add_u64 v[154:155], v[154:155], 0, s[8:9]
	v_lshl_add_u64 v[156:157], v[156:157], 0, s[8:9]
	v_lshl_add_u64 v[158:159], v[158:159], 0, s[8:9]
	v_lshl_add_u64 v[160:161], v[160:161], 0, s[8:9]
	v_lshl_add_u64 v[162:163], v[162:163], 0, s[8:9]
	s_cmp_lg_u32 s6, 0
	s_waitcnt vmcnt(7)
	ds_write_b128 v200, v[168:171]
	v_lshl_add_u64 v[168:169], v[148:149], 0, v[68:69]
	global_load_dwordx4 v[168:171], v[168:169], off offset:128
	s_waitcnt vmcnt(7)
	ds_write_b128 v200, v[172:175] offset:4608
	v_lshl_add_u64 v[172:173], v[150:151], 0, v[68:69]
	global_load_dwordx4 v[172:175], v[172:173], off offset:128
	s_waitcnt vmcnt(7)
	ds_write_b128 v200, v[176:179] offset:9216
	v_lshl_add_u64 v[176:177], v[152:153], 0, v[68:69]
	global_load_dwordx4 v[176:179], v[176:177], off offset:128
	s_waitcnt vmcnt(7)
	ds_write_b128 v200, v[180:183] offset:13824
	v_lshl_add_u64 v[180:181], v[154:155], 0, v[68:69]
	global_load_dwordx4 v[180:183], v[180:181], off offset:128
	s_waitcnt vmcnt(7)
	ds_write_b128 v200, v[184:187] offset:18432
	v_lshl_add_u64 v[184:185], v[156:157], 0, v[68:69]
	global_load_dwordx4 v[184:187], v[184:185], off offset:128
	s_waitcnt vmcnt(7)
	ds_write_b128 v200, v[188:191] offset:23040
	v_lshl_add_u64 v[188:189], v[158:159], 0, v[68:69]
	global_load_dwordx4 v[188:191], v[188:189], off offset:128
	s_waitcnt vmcnt(7)
	ds_write_b128 v200, v[192:195] offset:27648
	v_lshl_add_u64 v[192:193], v[160:161], 0, v[68:69]
	global_load_dwordx4 v[192:195], v[192:193], off offset:128
	s_waitcnt vmcnt(7)
	ds_write_b128 v200, v[196:199] offset:32256
	v_lshl_add_u64 v[196:197], v[162:163], 0, v[68:69]
	global_load_dwordx4 v[196:199], v[196:197], off offset:128
	s_setprio 0
	s_waitcnt lgkmcnt(0)
	s_barrier
	s_cbranch_scc1 .LBB0_1640
	s_and_b32 s40, s39, 2
	s_mulk_i32 s40, 0x4800
	v_add3_u32 v220, s40, v137, v164
	s_setprio 1
	v_add3_u32 v221, s40, v165, v164
	ds_read_b128 v[200:203], v220 offset:0
	ds_read_b128 v[204:207], v221 offset:18432
	ds_read_b128 v[212:215], v220 offset:4608
	ds_read_b128 v[208:211], v221 offset:23040
	s_waitcnt lgkmcnt(2)
	v_mfma_f32_32x32x16_bf16 v[34:49], v[200:203], v[204:207], v[34:49]
	ds_read_b128 v[216:219], v220 offset:32
	s_waitcnt lgkmcnt(2)
	v_mfma_f32_32x32x16_bf16 v[18:33], v[212:215], v[204:207], v[18:33]
	ds_read_b128 v[204:207], v221 offset:18464
	s_waitcnt lgkmcnt(2)
	v_mfma_f32_32x32x16_bf16 v[2:17], v[200:203], v[208:211], v[2:17]
	ds_read_b128 v[200:203], v220 offset:4640
	v_mfma_f32_32x32x16_bf16 v[50:65], v[212:215], v[208:211], v[50:65]
	ds_read_b128 v[208:211], v221 offset:23072
	s_waitcnt lgkmcnt(2)
	v_mfma_f32_32x32x16_bf16 v[34:49], v[216:219], v[204:207], v[34:49]
	ds_read_b128 v[212:215], v220 offset:64
	s_waitcnt lgkmcnt(2)
	v_mfma_f32_32x32x16_bf16 v[18:33], v[200:203], v[204:207], v[18:33]
	ds_read_b128 v[204:207], v221 offset:18496
	s_waitcnt lgkmcnt(2)
	v_mfma_f32_32x32x16_bf16 v[2:17], v[216:219], v[208:211], v[2:17]
	ds_read_b128 v[216:219], v220 offset:4672
	v_mfma_f32_32x32x16_bf16 v[50:65], v[200:203], v[208:211], v[50:65]
	ds_read_b128 v[208:211], v221 offset:23104
	s_waitcnt lgkmcnt(2)
	v_mfma_f32_32x32x16_bf16 v[34:49], v[212:215], v[204:207], v[34:49]
	ds_read_b128 v[200:203], v220 offset:96
	s_waitcnt lgkmcnt(2)
;     ...
;   for (int kt = 0; kt < nk; ++kt) {
;     const int kn = (kt + 1 < nk) ? kt + 1 : kt;
;     GM_LOAD2(kn * 64, kn * bkstep)
;     __builtin_amdgcn_sched_barrier(0);
;     const char* As = smem + (kt & 1) * 2 * TILE_B;
;     const char* Bs = As + TILE_B;
;     if constexpr (HOIST) {
;       bf16x8 fa0[4], fa1[4], fb0[4], fb1[4];
; #pragma unroll
;       for (int st = 0; st < 4; ++st) {
;         fa0[st] = *(const bf16x8*)(As + aoff + st * 32);
;         fb0[st] = *(const bf16x8*)(Bs + boff + st * 32);
;         fa1[st] = *(const bf16x8*)(As + aoff + 32 * LSTR + st * 32);
;         fb1[st] = *(const bf16x8*)(Bs + boff + 32 * LSTR + st * 32);
;       }
;       __builtin_amdgcn_sched_barrier(0);
; #pragma unroll
;       for (int st = 0; st < 4; ++st) {
;         acc[0][0] = mfma32(fa0[st], fb0[st], acc[0][0]);
;         acc[0][1] = mfma32(fa0[st], fb1[st], acc[0][1]);
;         acc[1][0] = mfma32(fa1[st], fb0[st], acc[1][0]);
;         acc[1][1] = mfma32(fa1[st], fb1[st], acc[1][1]);
;       }
;     } else {
; #pragma unroll
;       for (int st = 0; st < 4; ++st) {
;         bf16x8 a0 = *(const bf16x8*)(As + aoff + st * 32);
;         bf16x8 a1 = *(const bf16x8*)(As + aoff + 32 * LSTR + st * 32);
;         bf16x8 b0 = *(const bf16x8*)(Bs + boff + st * 32);
;         bf16x8 b1 = *(const bf16x8*)(Bs + boff + 32 * LSTR + st * 32);
;         acc[0][0] = mfma32(a0, b0, acc[0][0]);
;         acc[0][1] = mfma32(a0, b1, acc[0][1]);
;         acc[1][0] = mfma32(a1, b0, acc[1][0]);
;         acc[1][1] = mfma32(a1, b1, acc[1][1]);
;       }
;     }
;     __builtin_amdgcn_sched_barrier(0);
;     {
;       char* Ad = smem + ((kt + 1) & 1) * 2 * TILE_B;
;       GM_STORE(Ad)
;     }
;     __syncthreads();
; __device__ __forceinline__ void acc_to_lds(const f32x16 (&acc)[2][2], float* cs) {
;   const int tid = threadIdx.x, lane = tid & 63, wave = tid >> 6;
;   const int wm = wave >> 1, wn = wave & 1;
; #pragma unroll
;   for (int i = 0; i < 2; ++i)
; #pragma unroll
;     for (int j = 0; j < 2; ++j)
; #pragma unroll
;       for (int r = 0; r < 16; ++r) {
;         int row = wm * 64 + i * 32 + (r & 3) + 8 * (r >> 2) + 4 * (lane >> 5);
;         int col = wn * 64 + j * 32 + (lane & 31);
;         cs[row * CSTR + col] = acc[i][j][r];
;       }
;   __syncthreads();
	v_mfma_f32_32x32x16_bf16 v[18:33], v[216:219], v[204:207], v[18:33]
	ds_read_b128 v[204:207], v221 offset:18528
	s_waitcnt lgkmcnt(2)
	v_mfma_f32_32x32x16_bf16 v[2:17], v[212:215], v[208:211], v[2:17]
	ds_read_b128 v[212:215], v220 offset:4704
	v_mfma_f32_32x32x16_bf16 v[50:65], v[216:219], v[208:211], v[50:65]
	ds_read_b128 v[208:211], v221 offset:23136
	s_waitcnt lgkmcnt(2)
	v_mfma_f32_32x32x16_bf16 v[34:49], v[200:203], v[204:207], v[34:49]
	s_waitcnt lgkmcnt(1)
	v_mfma_f32_32x32x16_bf16 v[18:33], v[212:215], v[204:207], v[18:33]
	s_waitcnt lgkmcnt(0)
	v_mfma_f32_32x32x16_bf16 v[2:17], v[200:203], v[208:211], v[2:17]
	v_mfma_f32_32x32x16_bf16 v[50:65], v[212:215], v[208:211], v[50:65]
	s_add_i32 s39, s39, 2
	s_and_b32 s40, s39, 2
	s_mulk_i32 s40, 0x4800
	v_add_u32_e32 v200, s40, v135
	v_lshl_add_u64 v[148:149], v[148:149], 0, s[8:9]
	v_lshl_add_u64 v[150:151], v[150:151], 0, s[8:9]
	v_lshl_add_u64 v[152:153], v[152:153], 0, s[8:9]
	v_lshl_add_u64 v[154:155], v[154:155], 0, s[8:9]
	v_lshl_add_u64 v[156:157], v[156:157], 0, s[8:9]
	v_lshl_add_u64 v[158:159], v[158:159], 0, s[8:9]
	v_lshl_add_u64 v[160:161], v[160:161], 0, s[8:9]
	v_lshl_add_u64 v[162:163], v[162:163], 0, s[8:9]
	s_waitcnt vmcnt(7)
	ds_write_b128 v200, v[168:171]
	s_waitcnt vmcnt(6)
	ds_write_b128 v200, v[172:175] offset:4608
	s_waitcnt vmcnt(5)
	ds_write_b128 v200, v[176:179] offset:9216
	s_waitcnt vmcnt(4)
	ds_write_b128 v200, v[180:183] offset:13824
	s_waitcnt vmcnt(3)
	ds_write_b128 v200, v[184:187] offset:18432
	s_waitcnt vmcnt(2)
	ds_write_b128 v200, v[188:191] offset:23040
	s_waitcnt vmcnt(1)
	ds_write_b128 v200, v[192:195] offset:27648
	s_waitcnt vmcnt(0)
	ds_write_b128 v200, v[196:199] offset:32256
	s_setprio 0
	s_waitcnt lgkmcnt(0)
	s_barrier
	v_lshl_add_u64 v[180:181], v[162:163], 0, v[68:69]
	v_lshl_add_u64 v[176:177], v[160:161], 0, v[68:69]
	v_lshl_add_u64 v[172:173], v[158:159], 0, v[68:69]
	v_lshl_add_u64 v[168:169], v[156:157], 0, v[68:69]
	v_lshl_add_u64 v[160:161], v[154:155], 0, v[68:69]
	v_lshl_add_u64 v[156:157], v[152:153], 0, v[68:69]
	v_lshl_add_u64 v[152:153], v[150:151], 0, v[68:69]
	v_lshl_add_u64 v[148:149], v[148:149], 0, v[68:69]
	s_nop 0
	s_nop 0
	s_nop 0
	s_nop 0
	s_nop 0
	s_nop 0
	s_nop 0
	v_add3_u32 v68, s40, v137, v164
	s_setprio 1
	v_add3_u32 v212, s40, v165, v164
	ds_read_b128 v[184:187], v68 offset:0
	ds_read_b128 v[188:191], v212 offset:18432
	ds_read_b128 v[196:199], v68 offset:4608
	ds_read_b128 v[192:195], v212 offset:23040
	s_waitcnt lgkmcnt(2)
	v_mfma_f32_32x32x16_bf16 v[34:49], v[184:187], v[188:191], v[34:49]
	ds_read_b128 v[200:203], v68 offset:32
	s_waitcnt lgkmcnt(2)
	v_mfma_f32_32x32x16_bf16 v[18:33], v[196:199], v[188:191], v[18:33]
	ds_read_b128 v[188:191], v212 offset:18464
	s_waitcnt lgkmcnt(2)
	v_mfma_f32_32x32x16_bf16 v[2:17], v[184:187], v[192:195], v[2:17]
	ds_read_b128 v[184:187], v68 offset:4640
	v_mfma_f32_32x32x16_bf16 v[50:65], v[196:199], v[192:195], v[50:65]
	ds_read_b128 v[192:195], v212 offset:23072
	s_waitcnt lgkmcnt(2)
	v_mfma_f32_32x32x16_bf16 v[34:49], v[200:203], v[188:191], v[34:49]
	ds_read_b128 v[196:199], v68 offset:64
	s_waitcnt lgkmcnt(2)
	v_mfma_f32_32x32x16_bf16 v[18:33], v[184:187], v[188:191], v[18:33]
	ds_read_b128 v[188:191], v212 offset:18496
	s_waitcnt lgkmcnt(2)
	v_mfma_f32_32x32x16_bf16 v[2:17], v[200:203], v[192:195], v[2:17]
	ds_read_b128 v[200:203], v68 offset:4672
	v_mfma_f32_32x32x16_bf16 v[50:65], v[184:187], v[192:195], v[50:65]
	ds_read_b128 v[192:195], v212 offset:23104
	s_waitcnt lgkmcnt(2)
	v_mfma_f32_32x32x16_bf16 v[34:49], v[196:199], v[188:191], v[34:49]
	ds_read_b128 v[184:187], v68 offset:96
	s_waitcnt lgkmcnt(2)
	v_mfma_f32_32x32x16_bf16 v[18:33], v[200:203], v[188:191], v[18:33]
	ds_read_b128 v[188:191], v212 offset:18528
	s_waitcnt lgkmcnt(2)
	v_mfma_f32_32x32x16_bf16 v[2:17], v[196:199], v[192:195], v[2:17]
	ds_read_b128 v[196:199], v68 offset:4704
	v_mfma_f32_32x32x16_bf16 v[50:65], v[200:203], v[192:195], v[50:65]
	ds_read_b128 v[192:195], v212 offset:23136
	s_waitcnt lgkmcnt(2)
	v_mfma_f32_32x32x16_bf16 v[34:49], v[184:187], v[188:191], v[34:49]
	s_waitcnt lgkmcnt(1)
	v_mfma_f32_32x32x16_bf16 v[18:33], v[196:199], v[188:191], v[18:33]
	s_waitcnt lgkmcnt(0)
	v_mfma_f32_32x32x16_bf16 v[2:17], v[184:187], v[192:195], v[2:17]
	v_mfma_f32_32x32x16_bf16 v[50:65], v[196:199], v[192:195], v[50:65]
	s_setprio 0
	s_waitcnt lgkmcnt(0)
	s_barrier
	ds_write2_b32 v166, v34, v2 offset1:32
	ds_write2_b32 v166, v35, v3 offset0:132 offset1:164
	v_add_u32_e32 v2, 0x400, v166
	ds_write2_b32 v2, v36, v4 offset0:8 offset1:40
	ds_write2_b32 v2, v37, v5 offset0:140 offset1:172
	v_add_u32_e32 v2, 0x1000, v166
	ds_write2_b32 v2, v38, v6 offset0:32 offset1:64
	ds_write2_b32 v2, v39, v7 offset0:164 offset1:196
	v_add_u32_e32 v2, 0x1400, v166
	ds_write2_b32 v2, v40, v8 offset0:40 offset1:72
	ds_write2_b32 v2, v41, v9 offset0:172 offset1:204
	v_add_u32_e32 v2, 0x2000, v166
	ds_write2_b32 v2, v42, v10 offset0:64 offset1:96
	ds_write2_b32 v2, v43, v11 offset0:196 offset1:228
	v_add_u32_e32 v2, 0x2400, v166
	ds_write2_b32 v2, v44, v12 offset0:72 offset1:104
	ds_write2_b32 v2, v45, v13 offset0:204 offset1:236
	v_add_u32_e32 v2, 0x3000, v166
	ds_write2_b32 v2, v46, v14 offset0:96 offset1:128
	v_add_u32_e32 v2, 0x3200, v166
	ds_write2_b32 v2, v47, v15 offset0:100 offset1:132
	v_add_u32_e32 v2, 0x3400, v166
	ds_write2_b32 v2, v48, v16 offset0:104 offset1:136
	v_add_u32_e32 v2, 0x3600, v166
	ds_write2_b32 v2, v49, v17 offset0:108 offset1:140
	v_add_u32_e32 v2, 0x4000, v166
	ds_write2_b32 v2, v18, v50 offset0:128 offset1:160
	v_add_u32_e32 v2, 0x4400, v166
	ds_write2_b32 v2, v19, v51 offset0:4 offset1:36
	ds_write2_b32 v2, v20, v52 offset0:136 offset1:168
	v_add_u32_e32 v2, 0x4800, v166
	ds_write2_b32 v2, v21, v53 offset0:12 offset1:44
	v_add_u32_e32 v2, 0x5000, v166
	ds_write2_b32 v2, v22, v54 offset0:160 offset1:192
	v_add_u32_e32 v2, 0x5400, v166
	ds_write2_b32 v2, v23, v55 offset0:36 offset1:68
	ds_write2_b32 v2, v24, v56 offset0:168 offset1:200
	v_add_u32_e32 v2, 0x5800, v166
	ds_write2_b32 v2, v25, v57 offset0:44 offset1:76
	v_add_u32_e32 v2, 0x6000, v166
	ds_write2_b32 v2, v26, v58 offset0:192 offset1:224
	v_add_u32_e32 v2, 0x6400, v166
	ds_write2_b32 v2, v27, v59 offset0:68 offset1:100
	ds_write2_b32 v2, v28, v60 offset0:200 offset1:232
	v_add_u32_e32 v2, 0x6800, v166
	ds_write2_b32 v2, v29, v61 offset0:76 offset1:108
	v_add_u32_e32 v2, 0x7200, v166
	ds_write2_b32 v2, v30, v62 offset0:96 offset1:128
	v_add_u32_e32 v2, 0x7400, v166
	ds_write2_b32 v2, v31, v63 offset0:100 offset1:132
	v_add_u32_e32 v2, 0x7600, v166
	s_lshl_b32 s6, s38, 11
	ds_write2_b32 v2, v32, v64 offset0:104 offset1:136
	v_add_u32_e32 v2, 0x7800, v166
	v_lshl_add_u64 v[46:47], v[118:119], 0, s[6:7]
	ds_write2_b32 v2, v33, v65 offset0:108 offset1:140
	s_waitcnt lgkmcnt(0)
	s_barrier
; __device__ __forceinline__ void merge_tile(const Params& P, int l, int mt, int nt, char* smem) {
;     ...
;     const u16* gp = WSP(u16, OFF_G) + grow * 3072 + br * 1024 + nt * 128 + half * 64;
; #pragma unroll
;     for (int q = 0; q < 8; ++q) {
;       uint4 gq = *(const uint4*)(gp + q * 8);
;       float4 a = *(const float4*)(cs + r * CSTR + half * 64 + q * 8);
;       float4 c = *(const float4*)(cs + r * CSTR + half * 64 + q * 8 + 4);
;       macc[q * 8 + 0] += __uint_as_float(gq.x << 16) * a.x;
;       macc[q * 8 + 1] += __uint_as_float(gq.x & 0xffff0000u) * a.y;
;       macc[q * 8 + 2] += __uint_as_float(gq.y << 16) * a.z;
;       macc[q * 8 + 3] += __uint_as_float(gq.y & 0xffff0000u) * a.w;
;       macc[q * 8 + 4] += __uint_as_float(gq.z << 16) * c.x;
;       macc[q * 8 + 5] += __uint_as_float(gq.z & 0xffff0000u) * c.y;
;       macc[q * 8 + 6] += __uint_as_float(gq.w << 16) * c.z;
;       macc[q * 8 + 7] += __uint_as_float(gq.w & 0xffff0000u) * c.w;
;     }
;     __syncthreads();
	global_load_dwordx4 v[2:5], v[46:47], off
	global_load_dwordx4 v[6:9], v[46:47], off offset:16
	global_load_dwordx4 v[10:13], v[46:47], off offset:32
	global_load_dwordx4 v[14:17], v[46:47], off offset:48
	global_load_dwordx4 v[18:21], v[46:47], off offset:64
	global_load_dwordx4 v[22:25], v[46:47], off offset:80
	ds_read_b128 v[26:29], v167
	ds_read_b128 v[30:33], v167 offset:16
	ds_read_b128 v[34:37], v167 offset:32
	ds_read_b128 v[38:41], v167 offset:48
	global_load_dwordx4 v[42:45], v[46:47], off offset:112
	s_nop 0
	global_load_dwordx4 v[46:49], v[46:47], off offset:96
	s_add_i32 s38, s38, 1
	s_cmp_lg_u32 s38, 3
	s_waitcnt vmcnt(7)
	v_lshlrev_b32_e32 v50, 16, v2
	v_and_b32_e32 v51, 0xffff0000, v2
	v_lshlrev_b32_e32 v2, 16, v3
	v_and_b32_e32 v3, 0xffff0000, v3
	s_waitcnt lgkmcnt(3)
	v_pk_fma_f32 v[144:145], v[28:29], v[2:3], v[144:145]
	v_lshlrev_b32_e32 v2, 16, v4
	v_and_b32_e32 v3, 0xffff0000, v4
	s_waitcnt lgkmcnt(2)
	v_pk_fma_f32 v[142:143], v[30:31], v[2:3], v[142:143]
	v_lshlrev_b32_e32 v2, 16, v5
	v_and_b32_e32 v3, 0xffff0000, v5
	v_pk_fma_f32 v[140:141], v[32:33], v[2:3], v[140:141]
	s_waitcnt vmcnt(6)
	v_lshlrev_b32_e32 v2, 16, v6
	v_and_b32_e32 v3, 0xffff0000, v6
	s_waitcnt lgkmcnt(1)
	v_pk_fma_f32 v[138:139], v[34:35], v[2:3], v[138:139]
	v_lshlrev_b32_e32 v2, 16, v7
	v_and_b32_e32 v3, 0xffff0000, v7
	v_pk_fma_f32 v[132:133], v[36:37], v[2:3], v[132:133]
	v_lshlrev_b32_e32 v2, 16, v8
	v_and_b32_e32 v3, 0xffff0000, v8
	s_waitcnt lgkmcnt(0)
	v_pk_fma_f32 v[130:131], v[38:39], v[2:3], v[130:131]
	ds_read_b128 v[2:5], v167 offset:64
	v_lshlrev_b32_e32 v6, 16, v9
	v_and_b32_e32 v7, 0xffff0000, v9
	v_pk_fma_f32 v[128:129], v[40:41], v[6:7], v[128:129]
	ds_read_b128 v[6:9], v167 offset:80
	v_pk_fma_f32 v[146:147], v[26:27], v[50:51], v[146:147]
	s_waitcnt vmcnt(5)
	v_lshlrev_b32_e32 v26, 16, v10
	v_and_b32_e32 v27, 0xffff0000, v10
	s_waitcnt lgkmcnt(1)
	v_pk_fma_f32 v[126:127], v[2:3], v[26:27], v[126:127]
	v_lshlrev_b32_e32 v2, 16, v11
	v_and_b32_e32 v3, 0xffff0000, v11
	v_pk_fma_f32 v[124:125], v[4:5], v[2:3], v[124:125]
	v_lshlrev_b32_e32 v2, 16, v12
	v_and_b32_e32 v3, 0xffff0000, v12
	s_waitcnt lgkmcnt(0)
	v_pk_fma_f32 v[122:123], v[6:7], v[2:3], v[122:123]
	ds_read_b128 v[2:5], v167 offset:96
	v_lshlrev_b32_e32 v6, 16, v13
	v_and_b32_e32 v7, 0xffff0000, v13
	v_pk_fma_f32 v[120:121], v[8:9], v[6:7], v[120:121]
	ds_read_b128 v[6:9], v167 offset:112
	s_waitcnt vmcnt(4)
	v_lshlrev_b32_e32 v10, 16, v14
	v_and_b32_e32 v11, 0xffff0000, v14
	s_waitcnt lgkmcnt(1)
	v_pk_fma_f32 v[116:117], v[2:3], v[10:11], v[116:117]
	v_lshlrev_b32_e32 v2, 16, v15
	v_and_b32_e32 v3, 0xffff0000, v15
	v_pk_fma_f32 v[114:115], v[4:5], v[2:3], v[114:115]
	v_lshlrev_b32_e32 v2, 16, v16
	v_and_b32_e32 v3, 0xffff0000, v16
	s_waitcnt lgkmcnt(0)
	v_pk_fma_f32 v[112:113], v[6:7], v[2:3], v[112:113]
	ds_read_b128 v[2:5], v167 offset:128
	v_lshlrev_b32_e32 v6, 16, v17
	v_and_b32_e32 v7, 0xffff0000, v17
	v_pk_fma_f32 v[110:111], v[8:9], v[6:7], v[110:111]
	ds_read_b128 v[6:9], v167 offset:144
	s_waitcnt vmcnt(3)
	v_lshlrev_b32_e32 v10, 16, v18
	v_and_b32_e32 v11, 0xffff0000, v18
	s_waitcnt lgkmcnt(1)
	v_pk_fma_f32 v[106:107], v[2:3], v[10:11], v[106:107]
	v_lshlrev_b32_e32 v2, 16, v19
	v_and_b32_e32 v3, 0xffff0000, v19
	v_pk_fma_f32 v[104:105], v[4:5], v[2:3], v[104:105]
	v_lshlrev_b32_e32 v2, 16, v20
	v_and_b32_e32 v3, 0xffff0000, v20
	s_waitcnt lgkmcnt(0)
	v_pk_fma_f32 v[102:103], v[6:7], v[2:3], v[102:103]
	ds_read_b128 v[2:5], v167 offset:160
	v_lshlrev_b32_e32 v6, 16, v21
	v_and_b32_e32 v7, 0xffff0000, v21
	v_pk_fma_f32 v[100:101], v[8:9], v[6:7], v[100:101]
	ds_read_b128 v[6:9], v167 offset:176
	s_waitcnt vmcnt(2)
	v_lshlrev_b32_e32 v10, 16, v22
	v_and_b32_e32 v11, 0xffff0000, v22
	s_waitcnt lgkmcnt(1)
	v_pk_fma_f32 v[98:99], v[2:3], v[10:11], v[98:99]
	v_lshlrev_b32_e32 v2, 16, v23
	v_and_b32_e32 v3, 0xffff0000, v23
	v_pk_fma_f32 v[96:97], v[4:5], v[2:3], v[96:97]
	v_lshlrev_b32_e32 v2, 16, v24
	v_and_b32_e32 v3, 0xffff0000, v24
	s_waitcnt lgkmcnt(0)
	v_pk_fma_f32 v[94:95], v[6:7], v[2:3], v[94:95]
	ds_read_b128 v[2:5], v167 offset:192
	v_lshlrev_b32_e32 v6, 16, v25
	v_and_b32_e32 v7, 0xffff0000, v25
	v_pk_fma_f32 v[92:93], v[8:9], v[6:7], v[92:93]
	ds_read_b128 v[6:9], v167 offset:208
	s_waitcnt vmcnt(0)
	v_lshlrev_b32_e32 v10, 16, v46
	v_and_b32_e32 v11, 0xffff0000, v46
	s_waitcnt lgkmcnt(1)
	v_pk_fma_f32 v[90:91], v[2:3], v[10:11], v[90:91]
	v_lshlrev_b32_e32 v2, 16, v47
	v_and_b32_e32 v3, 0xffff0000, v47
	v_pk_fma_f32 v[88:89], v[4:5], v[2:3], v[88:89]
	v_lshlrev_b32_e32 v2, 16, v48
	v_and_b32_e32 v3, 0xffff0000, v48
	s_waitcnt lgkmcnt(0)
	v_pk_fma_f32 v[86:87], v[6:7], v[2:3], v[86:87]
	ds_read_b128 v[2:5], v167 offset:224
	v_lshlrev_b32_e32 v6, 16, v49
	v_and_b32_e32 v7, 0xffff0000, v49
	v_pk_fma_f32 v[84:85], v[8:9], v[6:7], v[84:85]
	ds_read_b128 v[6:9], v167 offset:240
	v_lshlrev_b32_e32 v10, 16, v42
	v_and_b32_e32 v11, 0xffff0000, v42
	s_waitcnt lgkmcnt(1)
	v_pk_fma_f32 v[82:83], v[2:3], v[10:11], v[82:83]
	v_lshlrev_b32_e32 v2, 16, v43
	v_and_b32_e32 v3, 0xffff0000, v43
	v_pk_fma_f32 v[80:81], v[4:5], v[2:3], v[80:81]
	v_lshlrev_b32_e32 v2, 16, v44
	v_and_b32_e32 v3, 0xffff0000, v44
	s_waitcnt lgkmcnt(0)
	v_pk_fma_f32 v[78:79], v[6:7], v[2:3], v[78:79]
	v_lshlrev_b32_e32 v2, 16, v45
	v_and_b32_e32 v3, 0xffff0000, v45
	v_pk_fma_f32 v[76:77], v[8:9], v[2:3], v[76:77]
	s_barrier
; __device__ __forceinline__ void store_row64_bf16(const float* v, u16* dst) {
; #pragma unroll
;   for (int q = 0; q < 8; ++q) {
;     uint4 o;
;     o.x = pack2(v[q * 8 + 0], v[q * 8 + 1]);
;     o.y = pack2(v[q * 8 + 2], v[q * 8 + 3]);
;     o.z = pack2(v[q * 8 + 4], v[q * 8 + 5]);
;     o.w = pack2(v[q * 8 + 6], v[q * 8 + 7]);
;     *(uint4*)(dst + q * 8) = o;
;   }
; }
; __device__ __forceinline__ void merge_tile(const Params& P, int l, int mt, int nt, char* smem) {
;     ...
;   store_row64_bf16(macc, WSP(u16, OFF_M) + grow * DM + nt * 128 + half * 64);
	s_cbranch_scc1 .LBB0_1639
	v_lshlrev_b64 v[2:3], 11, v[108:109]
	v_lshl_add_u64 v[2:3], s[4:5], 0, v[2:3]
	v_lshl_add_u64 v[2:3], s[12:13], 1, v[2:3]
	v_mov_b32_e32 v75, v69
	v_lshl_add_u64 v[6:7], v[2:3], 0, v[74:75]
	v_cvt_pk_bf16_f32 v2, v146, v147
	v_cvt_pk_bf16_f32 v3, v144, v145
	v_cvt_pk_bf16_f32 v4, v142, v143
	v_cvt_pk_bf16_f32 v5, v140, v141
	global_store_dwordx4 v[6:7], v[2:5], off
	v_readlane_b32 s40, v253, 37
	v_readlane_b32 s48, v253, 45
	v_cvt_pk_bf16_f32 v2, v138, v139
	v_cvt_pk_bf16_f32 v3, v132, v133
	v_cvt_pk_bf16_f32 v4, v130, v131
	v_cvt_pk_bf16_f32 v5, v128, v129
	global_store_dwordx4 v[6:7], v[2:5], off offset:16
	v_readlane_b32 s49, v253, 46
	v_readlane_b32 s41, v253, 38
	v_cvt_pk_bf16_f32 v2, v126, v127
	v_cvt_pk_bf16_f32 v3, v124, v125
	v_cvt_pk_bf16_f32 v4, v122, v123
	v_cvt_pk_bf16_f32 v5, v120, v121
	global_store_dwordx4 v[6:7], v[2:5], off offset:32
	v_readlane_b32 s42, v253, 39
	v_readlane_b32 s43, v253, 40
	v_cvt_pk_bf16_f32 v2, v116, v117
	v_cvt_pk_bf16_f32 v3, v114, v115
	v_cvt_pk_bf16_f32 v4, v112, v113
	v_cvt_pk_bf16_f32 v5, v110, v111
	global_store_dwordx4 v[6:7], v[2:5], off offset:48
	v_readlane_b32 s44, v253, 41
	v_readlane_b32 s45, v253, 42
	v_cvt_pk_bf16_f32 v2, v106, v107
	v_cvt_pk_bf16_f32 v3, v104, v105
	v_cvt_pk_bf16_f32 v4, v102, v103
	v_cvt_pk_bf16_f32 v5, v100, v101
	global_store_dwordx4 v[6:7], v[2:5], off offset:64
	v_readlane_b32 s46, v253, 43
	v_readlane_b32 s47, v253, 44
	v_cvt_pk_bf16_f32 v2, v98, v99
	v_cvt_pk_bf16_f32 v3, v96, v97
	v_cvt_pk_bf16_f32 v4, v94, v95
	v_cvt_pk_bf16_f32 v5, v92, v93
	global_store_dwordx4 v[6:7], v[2:5], off offset:80
	v_readlane_b32 s50, v253, 47
	v_readlane_b32 s51, v253, 48
	v_cvt_pk_bf16_f32 v2, v90, v91
	v_cvt_pk_bf16_f32 v3, v88, v89
	v_cvt_pk_bf16_f32 v4, v86, v87
	v_cvt_pk_bf16_f32 v5, v84, v85
	global_store_dwordx4 v[6:7], v[2:5], off offset:96
	v_readlane_b32 s52, v253, 49
	v_readlane_b32 s53, v253, 50
	v_cvt_pk_bf16_f32 v2, v82, v83
	v_cvt_pk_bf16_f32 v3, v80, v81
	v_cvt_pk_bf16_f32 v4, v78, v79
	v_cvt_pk_bf16_f32 v5, v76, v77
	global_store_dwordx4 v[6:7], v[2:5], off offset:112
	v_readlane_b32 s54, v253, 51
	v_readlane_b32 s55, v253, 52
	s_branch .LBB0_1636
